# v49 + same epilogue priority scheme on P3 / P4 / P7 (lead group 2 after align barrier, reset at re-stagger)
# baseline (speedup 1.0000x reference)
; #define PG8_BAR __builtin_amdgcn_s_barrier()
; template <class Epi, class SchedT, bool ALIGN_EPI, bool SP2>
; __device__ __forceinline__ void gemm_phase(LAS unsigned char* lds, const int ldk, const int nt, const SchedT& S, const Epi& E) {
;     ...
;         if constexpr (ALIGN_EPI) { if (wr == 0) PG8_BAR; }
;         E(acc, cur, wr, wc, fr, fq);
.Lp3e_align:
	s_and_b64 vcc, exec, s[44:45]
	s_cbranch_vccz .LBB0_537
	s_barrier
	s_setprio 2

; #define PG8_BAR __builtin_amdgcn_s_barrier()
; template <class Epi, class SchedT, bool ALIGN_EPI, bool SP2>
; __device__ __forceinline__ void gemm_phase(LAS unsigned char* lds, const int ldk, const int nt, const SchedT& S, const Epi& E) {
;     ...
;         cur = nxt; cA = nA; cB = nB; ++ui;
;         if constexpr (ALIGN_EPI) { if (wr == 1) PG8_BAR; }
.LBB0_588:
	s_setprio 0
	s_andn2_b64 vcc, exec, s[18:19]
	s_cbranch_vccnz .LBB0_527
	s_barrier
	s_setprio 1
	s_branch .LBB0_527

; #define PG8_STAGE(bufoff, gbase, voff) do { _Pragma("unroll") for (int _i = 0; _i < 2; ++_i) \
;         __builtin_amdgcn_global_load_lds((const __attribute__((address_space(1))) unsigned*)((const char*)(gbase) + (voff)[_i]), (LAS unsigned*)(lds + (bufoff) + ldsw + _i * 8192), 16, 0, 0); } while (0)
; #define PG8_LDA(dst, b, h) do { _Pragma("unroll") for (int m = 0; m < 4; ++m) _Pragma("unroll") for (int k = 0; k < 2; ++k) dst[m][k] = *(const LAS bf16x8*)(lds + PG8_SA(b, h) + aoff + m * 2048 + k * 1024); } while (0)
; #define PG8_LDB(dst, b, h) do { _Pragma("unroll") for (int n = 0; n < 2; ++n) _Pragma("unroll") for (int k = 0; k < 2; ++k) dst[n][k] = *(const LAS bf16x8*)(lds + PG8_SB(b, h) + boff + n * 2048 + k * 1024); } while (0)
; #define PG8_MMA(ai, bj, At, Bt) do { __builtin_amdgcn_s_setprio(1); _Pragma("unroll") for (int m = 0; m < 4; ++m) _Pragma("unroll") for (int n = 0; n < 2; ++n) _Pragma("unroll") for (int k = 0; k < 2; ++k) \
;         acc[ai][bj][m][n] = __builtin_amdgcn_mfma_f32_16x16x32_bf16(Bt[n][k], At[m][k], acc[ai][bj][m][n], 0, 0, 0); __builtin_amdgcn_s_setprio(0); } while (0)
; #define PG8_WAIT_V(n) asm volatile("s_waitcnt vmcnt(" #n ")" ::: "memory")
; #define PG8_WAIT_L(n) asm volatile("s_waitcnt lgkmcnt(" #n ")" ::: "memory")
; #define PG8_BAR __builtin_amdgcn_s_barrier()
; #define PG8_SCHED __builtin_amdgcn_sched_barrier(0)
; template <class Epi, class SchedT, bool ALIGN_EPI, bool SP2>
; __device__ __forceinline__ void gemm_phase(LAS unsigned char* lds, const int ldk, const int nt, const SchedT& S, const Epi& E) {
;     ...
;             PG8_LDB(B0, 0, 0); PG8_LDB(B1, 0, 1); PG8_SCHED; PG8_LDA(At, 0, 0); PG8_STAGE(PG8_SA(1, 1), a1 + hstep, voffA);
;             PG8_WAIT_V(8); PG8_WAIT_L(0); PG8_BAR; PG8_MMA(0, 0, At, B0); PG8_MMA(0, 1, At, B1); PG8_BAR; PG8_SCHED;
;             PG8_LDA(At, 0, 1); PG8_STAGE(PG8_SB(0, 0), b2, voffB); PG8_STAGE(PG8_SB(0, 1), b2 + hstepB, voffB); PG8_STAGE(PG8_SA(0, 0), a2, voffA);
;             PG8_WAIT_V(8); PG8_WAIT_L(0); PG8_BAR; PG8_MMA(1, 0, At, B0); PG8_MMA(1, 1, At, B1); PG8_BAR; PG8_SCHED;
.LBB0_668:
	s_add_u32 s36, s34, 0xfff80080
	s_addc_u32 s37, s35, -1
	s_add_i32 s51, 0, 0x10000
	s_cmp_eq_u32 s22, 28
	s_cselect_b32 s57, s1, s37
	s_cselect_b32 s56, s0, s36
	v_add_u32_e32 v144, s51, v147
	s_cselect_b32 s37, s55, s20
	s_cselect_b32 s36, s54, s13
	s_add_i32 s53, 0, 0x14000
	ds_read_b128 v[140:143], v144
	ds_read_b128 v[150:153], v144 offset:1024
	ds_read_b128 v[154:157], v144 offset:2048
	ds_read_b128 v[158:161], v144 offset:3072
	v_add_u32_e32 v144, s53, v147
	ds_read_b128 v[174:177], v144
	ds_read_b128 v[178:181], v144 offset:1024
	ds_read_b128 v[182:185], v144 offset:2048
	ds_read_b128 v[186:189], v144 offset:3072
	v_lshl_add_u64 v[144:145], s[34:35], 0, v[136:137]
	s_add_i32 m0, s17, 0xc000
	ds_read_b128 v[190:193], v149
	ds_read_b128 v[194:197], v149 offset:1024
	ds_read_b128 v[198:201], v149 offset:2048
	ds_read_b128 v[202:205], v149 offset:3072
	ds_read_b128 v[206:209], v149 offset:4096
	ds_read_b128 v[210:213], v149 offset:5120
	ds_read_b128 v[214:217], v149 offset:6144
	ds_read_b128 v[218:221], v149 offset:7168
	global_load_lds_dwordx4 v[144:145], off
	v_lshl_add_u64 v[144:145], s[34:35], 0, v[138:139]
	s_add_i32 m0, s17, 0xe000
	s_nop 0
	global_load_lds_dwordx4 v[144:145], off
	s_waitcnt vmcnt(8)
	s_waitcnt lgkmcnt(0)
	s_barrier
	s_waitcnt lgkmcnt(0)
	v_mfma_f32_16x16x32_bf16 v[126:129], v[140:143], v[190:193], v[126:129]
	v_mfma_f32_16x16x32_bf16 v[122:125], v[154:157], v[190:193], v[122:125]
	v_mfma_f32_16x16x32_bf16 v[110:113], v[140:143], v[198:201], v[110:113]
	v_mfma_f32_16x16x32_bf16 v[106:109], v[154:157], v[198:201], v[106:109]
	v_mfma_f32_16x16x32_bf16 v[94:97], v[140:143], v[206:209], v[94:97]
	v_mfma_f32_16x16x32_bf16 v[90:93], v[154:157], v[206:209], v[90:93]
	v_mfma_f32_16x16x32_bf16 v[78:81], v[140:143], v[214:217], v[78:81]
	v_mfma_f32_16x16x32_bf16 v[74:77], v[154:157], v[214:217], v[74:77]
	v_mfma_f32_16x16x32_bf16 v[126:129], v[150:153], v[194:197], v[126:129]
	v_mfma_f32_16x16x32_bf16 v[122:125], v[158:161], v[194:197], v[122:125]
	v_mfma_f32_16x16x32_bf16 v[110:113], v[150:153], v[202:205], v[110:113]
	v_mfma_f32_16x16x32_bf16 v[106:109], v[158:161], v[202:205], v[106:109]
	v_mfma_f32_16x16x32_bf16 v[94:97], v[150:153], v[210:213], v[94:97]
	v_mfma_f32_16x16x32_bf16 v[90:93], v[158:161], v[210:213], v[90:93]
	v_mfma_f32_16x16x32_bf16 v[78:81], v[150:153], v[218:221], v[78:81]
	v_mfma_f32_16x16x32_bf16 v[74:77], v[158:161], v[218:221], v[74:77]
	v_mfma_f32_16x16x32_bf16 v[118:121], v[174:177], v[190:193], v[118:121]
	v_mfma_f32_16x16x32_bf16 v[114:117], v[182:185], v[190:193], v[114:117]
	v_mfma_f32_16x16x32_bf16 v[102:105], v[174:177], v[198:201], v[102:105]
	v_mfma_f32_16x16x32_bf16 v[98:101], v[182:185], v[198:201], v[98:101]
	v_mfma_f32_16x16x32_bf16 v[86:89], v[174:177], v[206:209], v[86:89]
	v_mfma_f32_16x16x32_bf16 v[82:85], v[182:185], v[206:209], v[82:85]
	v_mfma_f32_16x16x32_bf16 v[70:73], v[174:177], v[214:217], v[70:73]
	v_mfma_f32_16x16x32_bf16 v[66:69], v[182:185], v[214:217], v[66:69]
	v_mfma_f32_16x16x32_bf16 v[118:121], v[178:181], v[194:197], v[118:121]
	v_mfma_f32_16x16x32_bf16 v[114:117], v[186:189], v[194:197], v[114:117]
	v_mfma_f32_16x16x32_bf16 v[102:105], v[178:181], v[202:205], v[102:105]
	v_mfma_f32_16x16x32_bf16 v[98:101], v[186:189], v[202:205], v[98:101]
	v_mfma_f32_16x16x32_bf16 v[86:89], v[178:181], v[210:213], v[86:89]
	v_mfma_f32_16x16x32_bf16 v[82:85], v[186:189], v[210:213], v[82:85]
	v_mfma_f32_16x16x32_bf16 v[70:73], v[178:181], v[218:221], v[70:73]
	v_mfma_f32_16x16x32_bf16 v[66:69], v[186:189], v[218:221], v[66:69]
	s_barrier
	s_add_i32 s51, s51, s61
	v_lshl_add_u64 v[144:145], s[36:37], 0, v[0:1]
	s_mov_b32 m0, s51
	ds_read_b128 v[190:193], v149 offset:16384
	ds_read_b128 v[194:197], v149 offset:17408
	ds_read_b128 v[198:201], v149 offset:18432
	ds_read_b128 v[202:205], v149 offset:19456
	ds_read_b128 v[206:209], v149 offset:20480
	ds_read_b128 v[210:213], v149 offset:21504
	ds_read_b128 v[214:217], v149 offset:22528
	ds_read_b128 v[218:221], v149 offset:23552
	global_load_lds_dwordx4 v[144:145], off
	s_add_i32 m0, s51, 0x2000
	s_add_u32 s86, s36, 0x20000
	v_lshl_add_u64 v[222:223], s[36:37], 0, v[134:135]
	s_addc_u32 s87, s37, 0
	s_add_i32 s51, s53, s61
	global_load_lds_dwordx4 v[222:223], off
	v_lshl_add_u64 v[224:225], s[86:87], 0, v[0:1]
	s_mov_b32 m0, s51
	v_lshl_add_u64 v[226:227], s[56:57], 0, v[132:133]
	global_load_lds_dwordx4 v[224:225], off
	v_lshl_add_u64 v[224:225], s[86:87], 0, v[134:135]
	s_add_i32 m0, s51, 0x2000
	s_nop 0
	global_load_lds_dwordx4 v[224:225], off
	v_lshl_add_u64 v[224:225], s[56:57], 0, v[130:131]
	s_mov_b32 m0, s17
	s_nop 0
	global_load_lds_dwordx4 v[224:225], off
	s_mov_b32 m0, s62
	s_nop 0
	global_load_lds_dwordx4 v[226:227], off
	s_waitcnt vmcnt(8)
	s_waitcnt lgkmcnt(0)
	s_barrier
; #define PG8_STAGE(bufoff, gbase, voff) do { _Pragma("unroll") for (int _i = 0; _i < 2; ++_i) \
;         __builtin_amdgcn_global_load_lds((const __attribute__((address_space(1))) unsigned*)((const char*)(gbase) + (voff)[_i]), (LAS unsigned*)(lds + (bufoff) + ldsw + _i * 8192), 16, 0, 0); } while (0)
; #define PG8_LDA(dst, b, h) do { _Pragma("unroll") for (int m = 0; m < 4; ++m) _Pragma("unroll") for (int k = 0; k < 2; ++k) dst[m][k] = *(const LAS bf16x8*)(lds + PG8_SA(b, h) + aoff + m * 2048 + k * 1024); } while (0)
; #define PG8_LDB(dst, b, h) do { _Pragma("unroll") for (int n = 0; n < 2; ++n) _Pragma("unroll") for (int k = 0; k < 2; ++k) dst[n][k] = *(const LAS bf16x8*)(lds + PG8_SB(b, h) + boff + n * 2048 + k * 1024); } while (0)
; #define PG8_MMA(ai, bj, At, Bt) do { __builtin_amdgcn_s_setprio(1); _Pragma("unroll") for (int m = 0; m < 4; ++m) _Pragma("unroll") for (int n = 0; n < 2; ++n) _Pragma("unroll") for (int k = 0; k < 2; ++k) \
;         acc[ai][bj][m][n] = __builtin_amdgcn_mfma_f32_16x16x32_bf16(Bt[n][k], At[m][k], acc[ai][bj][m][n], 0, 0, 0); __builtin_amdgcn_s_setprio(0); } while (0)
; #define PG8_WAIT_V(n) asm volatile("s_waitcnt vmcnt(" #n ")" ::: "memory")
; #define PG8_WAIT_L(n) asm volatile("s_waitcnt lgkmcnt(" #n ")" ::: "memory")
; #define PG8_BAR __builtin_amdgcn_s_barrier()
; #define PG8_SCHED __builtin_amdgcn_sched_barrier(0)
; template <class Epi, class SchedT, bool ALIGN_EPI, bool SP2>
; __device__ __forceinline__ void gemm_phase(LAS unsigned char* lds, const int ldk, const int nt, const SchedT& S, const Epi& E) {
;     ...
;             PG8_WAIT_V(8); PG8_WAIT_L(0); PG8_BAR; PG8_MMA(1, 0, At, B0); PG8_MMA(1, 1, At, B1); PG8_BAR; PG8_SCHED;
;             PG8_LDB(B0, 1, 0); PG8_LDB(B1, 1, 1); PG8_SCHED; PG8_LDA(At, 1, 0); PG8_STAGE(PG8_SA(0, 1), a2 + hstep, voffA);
;             PG8_WAIT_V(8); PG8_WAIT_L(0); PG8_BAR; PG8_MMA(0, 0, At, B0); PG8_MMA(0, 1, At, B1); PG8_BAR; PG8_SCHED;
	s_waitcnt lgkmcnt(0)
	v_mfma_f32_16x16x32_bf16 v[62:65], v[140:143], v[190:193], v[62:65]
	v_mfma_f32_16x16x32_bf16 v[58:61], v[154:157], v[190:193], v[58:61]
	v_mfma_f32_16x16x32_bf16 v[46:49], v[140:143], v[198:201], v[46:49]
	v_mfma_f32_16x16x32_bf16 v[42:45], v[154:157], v[198:201], v[42:45]
	v_mfma_f32_16x16x32_bf16 v[30:33], v[140:143], v[206:209], v[30:33]
	v_mfma_f32_16x16x32_bf16 v[26:29], v[154:157], v[206:209], v[26:29]
	v_mfma_f32_16x16x32_bf16 v[14:17], v[140:143], v[214:217], v[14:17]
	v_mfma_f32_16x16x32_bf16 v[10:13], v[154:157], v[214:217], v[10:13]
	v_mfma_f32_16x16x32_bf16 v[62:65], v[150:153], v[194:197], v[62:65]
	v_mfma_f32_16x16x32_bf16 v[58:61], v[158:161], v[194:197], v[58:61]
	v_mfma_f32_16x16x32_bf16 v[46:49], v[150:153], v[202:205], v[46:49]
	v_mfma_f32_16x16x32_bf16 v[42:45], v[158:161], v[202:205], v[42:45]
	v_mfma_f32_16x16x32_bf16 v[30:33], v[150:153], v[210:213], v[30:33]
	v_mfma_f32_16x16x32_bf16 v[26:29], v[158:161], v[210:213], v[26:29]
	v_mfma_f32_16x16x32_bf16 v[14:17], v[150:153], v[218:221], v[14:17]
	v_mfma_f32_16x16x32_bf16 v[10:13], v[158:161], v[218:221], v[10:13]
	v_mfma_f32_16x16x32_bf16 v[54:57], v[174:177], v[190:193], v[54:57]
	v_mfma_f32_16x16x32_bf16 v[50:53], v[182:185], v[190:193], v[50:53]
	v_mfma_f32_16x16x32_bf16 v[38:41], v[174:177], v[198:201], v[38:41]
	v_mfma_f32_16x16x32_bf16 v[34:37], v[182:185], v[198:201], v[34:37]
	v_mfma_f32_16x16x32_bf16 v[22:25], v[174:177], v[206:209], v[22:25]
	v_mfma_f32_16x16x32_bf16 v[18:21], v[182:185], v[206:209], v[18:21]
	v_mfma_f32_16x16x32_bf16 v[6:9], v[174:177], v[214:217], v[6:9]
	v_mfma_f32_16x16x32_bf16 v[2:5], v[182:185], v[214:217], v[2:5]
	v_mfma_f32_16x16x32_bf16 v[54:57], v[178:181], v[194:197], v[54:57]
	v_mfma_f32_16x16x32_bf16 v[50:53], v[186:189], v[194:197], v[50:53]
	v_mfma_f32_16x16x32_bf16 v[38:41], v[178:181], v[202:205], v[38:41]
	v_mfma_f32_16x16x32_bf16 v[34:37], v[186:189], v[202:205], v[34:37]
	v_mfma_f32_16x16x32_bf16 v[22:25], v[178:181], v[210:213], v[22:25]
	v_mfma_f32_16x16x32_bf16 v[18:21], v[186:189], v[210:213], v[18:21]
	v_mfma_f32_16x16x32_bf16 v[6:9], v[178:181], v[218:221], v[6:9]
	v_mfma_f32_16x16x32_bf16 v[2:5], v[186:189], v[218:221], v[2:5]
	s_barrier
	s_add_i32 s51, 0, 0x18000
	s_add_i32 s53, 0, 0x1c000
	v_add_u32_e32 v158, s51, v147
	v_add_u32_e32 v186, s53, v147
	ds_read_b128 v[140:143], v158
	ds_read_b128 v[150:153], v158 offset:1024
	ds_read_b128 v[154:157], v158 offset:2048
	ds_read_b128 v[158:161], v158 offset:3072
	ds_read_b128 v[174:177], v186
	ds_read_b128 v[178:181], v186 offset:1024
	ds_read_b128 v[182:185], v186 offset:2048
	ds_read_b128 v[186:189], v186 offset:3072
	s_add_u32 s56, s56, 0x80000
	s_addc_u32 s57, s57, 0
	s_mov_b32 m0, s63
	v_lshl_add_u64 v[228:229], s[56:57], 0, v[130:131]
	ds_read_b128 v[190:193], v149 offset:32768
	ds_read_b128 v[194:197], v149 offset:33792
	ds_read_b128 v[198:201], v149 offset:34816
	ds_read_b128 v[202:205], v149 offset:35840
	ds_read_b128 v[206:209], v149 offset:36864
	ds_read_b128 v[210:213], v149 offset:37888
	ds_read_b128 v[214:217], v149 offset:38912
	ds_read_b128 v[218:221], v149 offset:39936
	global_load_lds_dwordx4 v[228:229], off
	v_lshl_add_u64 v[228:229], s[56:57], 0, v[132:133]
	s_mov_b32 m0, s81
	s_nop 0
	global_load_lds_dwordx4 v[228:229], off
	s_waitcnt vmcnt(8)
	s_waitcnt lgkmcnt(0)
	s_barrier
	s_waitcnt lgkmcnt(0)
	v_mfma_f32_16x16x32_bf16 v[126:129], v[140:143], v[190:193], v[126:129]
	v_mfma_f32_16x16x32_bf16 v[122:125], v[154:157], v[190:193], v[122:125]
	v_mfma_f32_16x16x32_bf16 v[110:113], v[140:143], v[198:201], v[110:113]
	v_mfma_f32_16x16x32_bf16 v[106:109], v[154:157], v[198:201], v[106:109]
	v_mfma_f32_16x16x32_bf16 v[94:97], v[140:143], v[206:209], v[94:97]
	v_mfma_f32_16x16x32_bf16 v[90:93], v[154:157], v[206:209], v[90:93]
	v_mfma_f32_16x16x32_bf16 v[78:81], v[140:143], v[214:217], v[78:81]
	v_mfma_f32_16x16x32_bf16 v[74:77], v[154:157], v[214:217], v[74:77]
	v_mfma_f32_16x16x32_bf16 v[126:129], v[150:153], v[194:197], v[126:129]
	v_mfma_f32_16x16x32_bf16 v[122:125], v[158:161], v[194:197], v[122:125]
	v_mfma_f32_16x16x32_bf16 v[110:113], v[150:153], v[202:205], v[110:113]
	v_mfma_f32_16x16x32_bf16 v[106:109], v[158:161], v[202:205], v[106:109]
	v_mfma_f32_16x16x32_bf16 v[94:97], v[150:153], v[210:213], v[94:97]
	v_mfma_f32_16x16x32_bf16 v[90:93], v[158:161], v[210:213], v[90:93]
	v_mfma_f32_16x16x32_bf16 v[78:81], v[150:153], v[218:221], v[78:81]
	v_mfma_f32_16x16x32_bf16 v[74:77], v[158:161], v[218:221], v[74:77]
	v_mfma_f32_16x16x32_bf16 v[118:121], v[174:177], v[190:193], v[118:121]
	v_mfma_f32_16x16x32_bf16 v[114:117], v[182:185], v[190:193], v[114:117]
	v_mfma_f32_16x16x32_bf16 v[102:105], v[174:177], v[198:201], v[102:105]
	v_mfma_f32_16x16x32_bf16 v[98:101], v[182:185], v[198:201], v[98:101]
	v_mfma_f32_16x16x32_bf16 v[86:89], v[174:177], v[206:209], v[86:89]
	v_mfma_f32_16x16x32_bf16 v[82:85], v[182:185], v[206:209], v[82:85]
	v_mfma_f32_16x16x32_bf16 v[70:73], v[174:177], v[214:217], v[70:73]
	v_mfma_f32_16x16x32_bf16 v[66:69], v[182:185], v[214:217], v[66:69]
	v_mfma_f32_16x16x32_bf16 v[118:121], v[178:181], v[194:197], v[118:121]
	v_mfma_f32_16x16x32_bf16 v[114:117], v[186:189], v[194:197], v[114:117]
	v_mfma_f32_16x16x32_bf16 v[102:105], v[178:181], v[202:205], v[102:105]
	v_mfma_f32_16x16x32_bf16 v[98:101], v[186:189], v[202:205], v[98:101]
	v_mfma_f32_16x16x32_bf16 v[86:89], v[178:181], v[210:213], v[86:89]
	v_mfma_f32_16x16x32_bf16 v[82:85], v[186:189], v[210:213], v[82:85]
	v_mfma_f32_16x16x32_bf16 v[70:73], v[178:181], v[218:221], v[70:73]
	v_mfma_f32_16x16x32_bf16 v[66:69], v[186:189], v[218:221], v[66:69]
	s_barrier
; #define PG8_STAGE(bufoff, gbase, voff) do { _Pragma("unroll") for (int _i = 0; _i < 2; ++_i) \
;         __builtin_amdgcn_global_load_lds((const __attribute__((address_space(1))) unsigned*)((const char*)(gbase) + (voff)[_i]), (LAS unsigned*)(lds + (bufoff) + ldsw + _i * 8192), 16, 0, 0); } while (0)
; #define PG8_LDA(dst, b, h) do { _Pragma("unroll") for (int m = 0; m < 4; ++m) _Pragma("unroll") for (int k = 0; k < 2; ++k) dst[m][k] = *(const LAS bf16x8*)(lds + PG8_SA(b, h) + aoff + m * 2048 + k * 1024); } while (0)
; #define PG8_MMA(ai, bj, At, Bt) do { __builtin_amdgcn_s_setprio(1); _Pragma("unroll") for (int m = 0; m < 4; ++m) _Pragma("unroll") for (int n = 0; n < 2; ++n) _Pragma("unroll") for (int k = 0; k < 2; ++k) \
;         acc[ai][bj][m][n] = __builtin_amdgcn_mfma_f32_16x16x32_bf16(Bt[n][k], At[m][k], acc[ai][bj][m][n], 0, 0, 0); __builtin_amdgcn_s_setprio(0); } while (0)
; #define PG8_WAIT_V(n) asm volatile("s_waitcnt vmcnt(" #n ")" ::: "memory")
; #define PG8_WAIT_L(n) asm volatile("s_waitcnt lgkmcnt(" #n ")" ::: "memory")
; #define PG8_BAR __builtin_amdgcn_s_barrier()
; #define PG8_SCHED __builtin_amdgcn_sched_barrier(0)
; template <class Epi, class SchedT, bool ALIGN_EPI, bool SP2>
; __device__ __forceinline__ void gemm_phase(LAS unsigned char* lds, const int ldk, const int nt, const SchedT& S, const Epi& E) {
;     ...
;             PG8_LDA(At, 1, 1); PG8_STAGE(PG8_SB(1, 0), b3, voffB); PG8_STAGE(PG8_SB(1, 1), b3 + hstepB, voffB); PG8_STAGE(PG8_SA(1, 0), a3, voffA);
;             PG8_WAIT_V(8); PG8_WAIT_L(0); PG8_BAR; PG8_MMA(1, 0, At, B0); PG8_MMA(1, 1, At, B1); PG8_BAR; PG8_SCHED;
;     __device__ __forceinline__ void operator()(f32x4 (&acc)[2][2][4][2], const Unit& u, int wr, int wc, int fr, int fq) const {
;     ...
;                 const int row = row0 + ai * HALF + m * 16; float sq = 0.f;
; #pragma unroll
;                 for (int bj = 0; bj < 2; ++bj) {
;                     const size_t off = (size_t)row * D + col0 + bj * 32;
;                     const u32x4 xw = *(const u32x4*)(xin + off);
	s_add_i32 s51, s51, s61
	v_lshl_add_u64 v[144:145], v[144:145], 0, s[24:25]
	s_mov_b32 m0, s51
	ds_read_b128 v[190:193], v149 offset:49152
	ds_read_b128 v[194:197], v149 offset:50176
	ds_read_b128 v[198:201], v149 offset:51200
	ds_read_b128 v[202:205], v149 offset:52224
	ds_read_b128 v[206:209], v149 offset:53248
	ds_read_b128 v[210:213], v149 offset:54272
	ds_read_b128 v[214:217], v149 offset:55296
	ds_read_b128 v[218:221], v149 offset:56320
	global_load_lds_dwordx4 v[144:145], off
	s_add_i32 m0, s51, 0x2000
	s_add_u32 s36, s36, 0x20080
	v_lshl_add_u64 v[144:145], v[222:223], 0, s[24:25]
	s_addc_u32 s37, s37, 0
	s_add_i32 s51, s53, s61
	global_load_lds_dwordx4 v[144:145], off
	v_lshl_add_u64 v[144:145], s[36:37], 0, v[0:1]
	s_mov_b32 m0, s51
	s_nop 0
	global_load_lds_dwordx4 v[144:145], off
	v_lshl_add_u64 v[144:145], s[36:37], 0, v[134:135]
	s_add_i32 m0, s51, 0x2000
	s_nop 0
	global_load_lds_dwordx4 v[144:145], off
	v_lshl_add_u64 v[144:145], v[224:225], 0, s[24:25]
	s_mov_b32 m0, s83
	s_nop 0
	global_load_lds_dwordx4 v[144:145], off
	v_lshl_add_u64 v[144:145], v[226:227], 0, s[24:25]
	s_mov_b32 m0, s84
	s_nop 0
	global_load_lds_dwordx4 v[144:145], off
	s_waitcnt vmcnt(8)
	s_waitcnt lgkmcnt(0)
	s_barrier
	s_waitcnt lgkmcnt(0)
	v_mfma_f32_16x16x32_bf16 v[62:65], v[140:143], v[190:193], v[62:65]
	v_mfma_f32_16x16x32_bf16 v[58:61], v[154:157], v[190:193], v[58:61]
	v_mfma_f32_16x16x32_bf16 v[46:49], v[140:143], v[198:201], v[46:49]
	v_mfma_f32_16x16x32_bf16 v[42:45], v[154:157], v[198:201], v[42:45]
	v_mfma_f32_16x16x32_bf16 v[30:33], v[140:143], v[206:209], v[30:33]
	v_mfma_f32_16x16x32_bf16 v[26:29], v[154:157], v[206:209], v[26:29]
	v_mfma_f32_16x16x32_bf16 v[14:17], v[140:143], v[214:217], v[14:17]
	v_mfma_f32_16x16x32_bf16 v[10:13], v[154:157], v[214:217], v[10:13]
	v_mfma_f32_16x16x32_bf16 v[62:65], v[150:153], v[194:197], v[62:65]
	v_mfma_f32_16x16x32_bf16 v[58:61], v[158:161], v[194:197], v[58:61]
	v_mfma_f32_16x16x32_bf16 v[46:49], v[150:153], v[202:205], v[46:49]
	v_mfma_f32_16x16x32_bf16 v[42:45], v[158:161], v[202:205], v[42:45]
	v_mfma_f32_16x16x32_bf16 v[30:33], v[150:153], v[210:213], v[30:33]
	v_mfma_f32_16x16x32_bf16 v[26:29], v[158:161], v[210:213], v[26:29]
	v_mfma_f32_16x16x32_bf16 v[14:17], v[150:153], v[218:221], v[14:17]
	v_mfma_f32_16x16x32_bf16 v[10:13], v[158:161], v[218:221], v[10:13]
	v_mfma_f32_16x16x32_bf16 v[54:57], v[174:177], v[190:193], v[54:57]
	v_mfma_f32_16x16x32_bf16 v[50:53], v[182:185], v[190:193], v[50:53]
	v_mfma_f32_16x16x32_bf16 v[38:41], v[174:177], v[198:201], v[38:41]
	v_mfma_f32_16x16x32_bf16 v[34:37], v[182:185], v[198:201], v[34:37]
	v_mfma_f32_16x16x32_bf16 v[22:25], v[174:177], v[206:209], v[22:25]
	v_mfma_f32_16x16x32_bf16 v[18:21], v[182:185], v[206:209], v[18:21]
	v_mfma_f32_16x16x32_bf16 v[6:9], v[174:177], v[214:217], v[6:9]
	v_mfma_f32_16x16x32_bf16 v[2:5], v[182:185], v[214:217], v[2:5]
	v_mfma_f32_16x16x32_bf16 v[54:57], v[178:181], v[194:197], v[54:57]
	v_mfma_f32_16x16x32_bf16 v[50:53], v[186:189], v[194:197], v[50:53]
	v_mfma_f32_16x16x32_bf16 v[38:41], v[178:181], v[202:205], v[38:41]
	v_mfma_f32_16x16x32_bf16 v[34:37], v[186:189], v[202:205], v[34:37]
	v_mfma_f32_16x16x32_bf16 v[22:25], v[178:181], v[210:213], v[22:25]
	v_mfma_f32_16x16x32_bf16 v[18:21], v[186:189], v[210:213], v[18:21]
	v_mfma_f32_16x16x32_bf16 v[6:9], v[178:181], v[218:221], v[6:9]
	v_mfma_f32_16x16x32_bf16 v[2:5], v[186:189], v[218:221], v[2:5]
	s_barrier
	s_add_i32 s22, s22, 2
	s_add_u32 s34, s34, 0x100
	s_addc_u32 s35, s35, 0
	s_add_u32 s13, s13, 0x100
	s_addc_u32 s20, s20, 0
	s_cmp_gt_u32 s22, 29
	s_cbranch_scc0 .LBB0_668
	v_lshl_add_u32 v142, s16, 8, v146
	v_lshl_or_b32 v140, s12, 8, v148
	v_lshlrev_b32_e32 v141, 12, v142
	v_lshl_add_u32 v150, v140, 1, v141
	v_add_u32_e32 v151, 0x10000, v150
	v_add_u32_e32 v152, 0x20000, v150
	v_add_u32_e32 v153, 0x30000, v150
	v_add_u32_e32 v154, 0x80000, v150
	v_add_u32_e32 v155, 0x90000, v150
	v_add_u32_e32 v156, 0xa0000, v150
	v_add_u32_e32 v157, 0xb0000, v150
	global_load_dwordx4 v[174:177], v150, s[42:43]
	global_load_dwordx4 v[178:181], v150, s[42:43] offset:64
	global_load_dwordx4 v[182:185], v151, s[42:43]
	global_load_dwordx4 v[186:189], v151, s[42:43] offset:64
	global_load_dwordx4 v[190:193], v152, s[42:43]
	global_load_dwordx4 v[194:197], v152, s[42:43] offset:64
	global_load_dwordx4 v[198:201], v153, s[42:43]
	global_load_dwordx4 v[202:205], v153, s[42:43] offset:64
	global_load_dwordx4 v[206:209], v154, s[42:43]
	global_load_dwordx4 v[210:213], v154, s[42:43] offset:64
	global_load_dwordx4 v[214:217], v155, s[42:43]
	global_load_dwordx4 v[218:221], v155, s[42:43] offset:64
	global_load_dwordx4 v[222:225], v156, s[42:43]
	global_load_dwordx4 v[226:229], v156, s[42:43] offset:64
	global_load_dwordx4 v[230:233], v157, s[42:43]
	global_load_dwordx4 v[234:237], v157, s[42:43] offset:64
	s_lshl_b32 s56, s12, 4
	s_lshl_b32 s22, s82, 2
	s_add_i32 s56, s56, s22
	v_lshl_add_u32 v158, v142, 7, s56
	v_add_u32_e32 v159, 0x1000, v158
	v_add_u32_e32 v160, 0x4000, v158
	v_add_u32_e32 v161, 0x5000, v158
	v_xor_b32_e32 v239, 16, v241
	v_xor_b32_e32 v252, 32, v241
	v_lshlrev_b32_e32 v239, 2, v239
	v_lshlrev_b32_e32 v252, 2, v252
	s_and_b64 vcc, exec, s[48:49]
	s_cbranch_vccz .LBB0_671
	s_barrier
	s_setprio 2
; __device__ __forceinline__ float bf_lo(unsigned w) { return __uint_as_float(w << 16); }
; __device__ __forceinline__ float bf_hi(unsigned w) { return __uint_as_float(w & 0xffff0000u); }
; __device__ __forceinline__ u32x4 pack8(f32x4 a, f32x4 b) { u32x4 w; w.x = cvt_pk_bf16(a[0], a[1]); w.y = cvt_pk_bf16(a[2], a[3]); w.z = cvt_pk_bf16(b[0], b[1]); w.w = cvt_pk_bf16(b[2], b[3]); return w; }
;     __device__ __forceinline__ void operator()(f32x4 (&acc)[2][2][4][2], const Unit& u, int wr, int wc, int fr, int fq) const {
;     ...
;                 const int row = row0 + ai * HALF + m * 16; float sq = 0.f;
; #pragma unroll
;                 for (int bj = 0; bj < 2; ++bj) {
;                     const size_t off = (size_t)row * D + col0 + bj * 32;
;                     const u32x4 xw = *(const u32x4*)(xin + off);
;                     const f32x4 v0 = acc[ai][bj][m][0] + (f32x4){bf_lo(xw.x), bf_hi(xw.x), bf_lo(xw.y), bf_hi(xw.y)}, v1 = acc[ai][bj][m][1] + (f32x4){bf_lo(xw.z), bf_hi(xw.z), bf_lo(xw.w), bf_hi(xw.w)};
;                     *(u32x4*)(xb + off) = pack8(v0, v1);
;                     sq += (v0[0] * v0[0] + v0[1] * v0[1]) + (v0[2] * v0[2] + v0[3] * v0[3]) + (v1[0] * v1[0] + v1[1] * v1[1]) + (v1[2] * v1[2] + v1[3] * v1[3]);
.LBB0_671:
	s_waitcnt vmcnt(15)
	v_lshlrev_b32_e32 v246, 16, v174
	v_and_b32_e32 v247, 0xffff0000, v174
	v_lshlrev_b32_e32 v248, 16, v175
	v_and_b32_e32 v249, 0xffff0000, v175
	v_pk_add_f32 v[126:127], v[126:127], v[246:247]
	v_pk_add_f32 v[128:129], v[128:129], v[248:249]
	v_lshlrev_b32_e32 v246, 16, v176
	v_and_b32_e32 v247, 0xffff0000, v176
	v_lshlrev_b32_e32 v248, 16, v177
	v_and_b32_e32 v249, 0xffff0000, v177
	v_pk_add_f32 v[122:123], v[122:123], v[246:247]
	v_pk_add_f32 v[124:125], v[124:125], v[248:249]
	v_cvt_pk_bf16_f32 v174, v126, v127
	v_cvt_pk_bf16_f32 v175, v128, v129
	v_cvt_pk_bf16_f32 v176, v122, v123
	v_cvt_pk_bf16_f32 v177, v124, v125
	global_store_dwordx4 v150, v[174:177], s[44:45]
	v_pk_mul_f32 v[250:251], v[126:127], v[126:127]
	v_pk_fma_f32 v[250:251], v[128:129], v[128:129], v[250:251]
	v_pk_fma_f32 v[250:251], v[122:123], v[122:123], v[250:251]
	v_pk_fma_f32 v[250:251], v[124:125], v[124:125], v[250:251]
	s_waitcnt vmcnt(15)
	v_lshlrev_b32_e32 v246, 16, v178
	v_and_b32_e32 v247, 0xffff0000, v178
	v_lshlrev_b32_e32 v248, 16, v179
	v_and_b32_e32 v249, 0xffff0000, v179
	v_pk_add_f32 v[118:119], v[118:119], v[246:247]
	v_pk_add_f32 v[120:121], v[120:121], v[248:249]
	v_lshlrev_b32_e32 v246, 16, v180
	v_and_b32_e32 v247, 0xffff0000, v180
	v_lshlrev_b32_e32 v248, 16, v181
	v_and_b32_e32 v249, 0xffff0000, v181
	v_pk_add_f32 v[114:115], v[114:115], v[246:247]
	v_pk_add_f32 v[116:117], v[116:117], v[248:249]
	v_cvt_pk_bf16_f32 v178, v118, v119
	v_cvt_pk_bf16_f32 v179, v120, v121
	v_cvt_pk_bf16_f32 v180, v114, v115
	v_cvt_pk_bf16_f32 v181, v116, v117
	global_store_dwordx4 v150, v[178:181], s[44:45] offset:64
	v_pk_fma_f32 v[250:251], v[118:119], v[118:119], v[250:251]
	v_pk_fma_f32 v[250:251], v[120:121], v[120:121], v[250:251]
	v_pk_fma_f32 v[250:251], v[114:115], v[114:115], v[250:251]
	v_pk_fma_f32 v[250:251], v[116:117], v[116:117], v[250:251]
	v_add_f32_e32 v140, v250, v251
	s_waitcnt vmcnt(15)
	v_lshlrev_b32_e32 v246, 16, v182
	v_and_b32_e32 v247, 0xffff0000, v182
	v_lshlrev_b32_e32 v248, 16, v183
	v_and_b32_e32 v249, 0xffff0000, v183
	v_pk_add_f32 v[110:111], v[110:111], v[246:247]
	v_pk_add_f32 v[112:113], v[112:113], v[248:249]
	v_lshlrev_b32_e32 v246, 16, v184
	v_and_b32_e32 v247, 0xffff0000, v184
	v_lshlrev_b32_e32 v248, 16, v185
	v_and_b32_e32 v249, 0xffff0000, v185
	v_pk_add_f32 v[106:107], v[106:107], v[246:247]
	v_pk_add_f32 v[108:109], v[108:109], v[248:249]
	v_cvt_pk_bf16_f32 v182, v110, v111
	v_cvt_pk_bf16_f32 v183, v112, v113
	v_cvt_pk_bf16_f32 v184, v106, v107
	v_cvt_pk_bf16_f32 v185, v108, v109
	global_store_dwordx4 v151, v[182:185], s[44:45]
	v_pk_mul_f32 v[250:251], v[110:111], v[110:111]
	v_pk_fma_f32 v[250:251], v[112:113], v[112:113], v[250:251]
	v_pk_fma_f32 v[250:251], v[106:107], v[106:107], v[250:251]
	v_pk_fma_f32 v[250:251], v[108:109], v[108:109], v[250:251]
	s_waitcnt vmcnt(15)
	v_lshlrev_b32_e32 v246, 16, v186
	v_and_b32_e32 v247, 0xffff0000, v186
	v_lshlrev_b32_e32 v248, 16, v187
	v_and_b32_e32 v249, 0xffff0000, v187
	v_pk_add_f32 v[102:103], v[102:103], v[246:247]
	v_pk_add_f32 v[104:105], v[104:105], v[248:249]
	v_lshlrev_b32_e32 v246, 16, v188
	v_and_b32_e32 v247, 0xffff0000, v188
	v_lshlrev_b32_e32 v248, 16, v189
	v_and_b32_e32 v249, 0xffff0000, v189
	v_pk_add_f32 v[98:99], v[98:99], v[246:247]
	v_pk_add_f32 v[100:101], v[100:101], v[248:249]
	v_cvt_pk_bf16_f32 v186, v102, v103
	v_cvt_pk_bf16_f32 v187, v104, v105
	v_cvt_pk_bf16_f32 v188, v98, v99
	v_cvt_pk_bf16_f32 v189, v100, v101
	global_store_dwordx4 v151, v[186:189], s[44:45] offset:64
	v_pk_fma_f32 v[250:251], v[102:103], v[102:103], v[250:251]
	v_pk_fma_f32 v[250:251], v[104:105], v[104:105], v[250:251]
	v_pk_fma_f32 v[250:251], v[98:99], v[98:99], v[250:251]
	v_pk_fma_f32 v[250:251], v[100:101], v[100:101], v[250:251]
	v_add_f32_e32 v141, v250, v251
	s_waitcnt vmcnt(15)
	v_lshlrev_b32_e32 v246, 16, v190
	v_and_b32_e32 v247, 0xffff0000, v190
	v_lshlrev_b32_e32 v248, 16, v191
	v_and_b32_e32 v249, 0xffff0000, v191
	v_pk_add_f32 v[94:95], v[94:95], v[246:247]
	v_pk_add_f32 v[96:97], v[96:97], v[248:249]
	v_lshlrev_b32_e32 v246, 16, v192
	v_and_b32_e32 v247, 0xffff0000, v192
	v_lshlrev_b32_e32 v248, 16, v193
	v_and_b32_e32 v249, 0xffff0000, v193
	v_pk_add_f32 v[90:91], v[90:91], v[246:247]
	v_pk_add_f32 v[92:93], v[92:93], v[248:249]
	v_cvt_pk_bf16_f32 v190, v94, v95
	v_cvt_pk_bf16_f32 v191, v96, v97
	v_cvt_pk_bf16_f32 v192, v90, v91
	v_cvt_pk_bf16_f32 v193, v92, v93
	global_store_dwordx4 v152, v[190:193], s[44:45]
	v_pk_mul_f32 v[250:251], v[94:95], v[94:95]
	v_pk_fma_f32 v[250:251], v[96:97], v[96:97], v[250:251]
	v_pk_fma_f32 v[250:251], v[90:91], v[90:91], v[250:251]
	v_pk_fma_f32 v[250:251], v[92:93], v[92:93], v[250:251]
	s_waitcnt vmcnt(15)
	v_lshlrev_b32_e32 v246, 16, v194
	v_and_b32_e32 v247, 0xffff0000, v194
	v_lshlrev_b32_e32 v248, 16, v195
	v_and_b32_e32 v249, 0xffff0000, v195
	v_pk_add_f32 v[86:87], v[86:87], v[246:247]
	v_pk_add_f32 v[88:89], v[88:89], v[248:249]
	v_lshlrev_b32_e32 v246, 16, v196
	v_and_b32_e32 v247, 0xffff0000, v196
	v_lshlrev_b32_e32 v248, 16, v197
	v_and_b32_e32 v249, 0xffff0000, v197
	v_pk_add_f32 v[82:83], v[82:83], v[246:247]
	v_pk_add_f32 v[84:85], v[84:85], v[248:249]
	v_cvt_pk_bf16_f32 v194, v86, v87
	v_cvt_pk_bf16_f32 v195, v88, v89
	v_cvt_pk_bf16_f32 v196, v82, v83
	v_cvt_pk_bf16_f32 v197, v84, v85
	global_store_dwordx4 v152, v[194:197], s[44:45] offset:64
	v_pk_fma_f32 v[250:251], v[86:87], v[86:87], v[250:251]
	v_pk_fma_f32 v[250:251], v[88:89], v[88:89], v[250:251]
	v_pk_fma_f32 v[250:251], v[82:83], v[82:83], v[250:251]
	v_pk_fma_f32 v[250:251], v[84:85], v[84:85], v[250:251]
	v_add_f32_e32 v142, v250, v251
	s_waitcnt vmcnt(15)
; __device__ __forceinline__ float bf_lo(unsigned w) { return __uint_as_float(w << 16); }
; __device__ __forceinline__ float bf_hi(unsigned w) { return __uint_as_float(w & 0xffff0000u); }
; __device__ __forceinline__ u32x4 pack8(f32x4 a, f32x4 b) { u32x4 w; w.x = cvt_pk_bf16(a[0], a[1]); w.y = cvt_pk_bf16(a[2], a[3]); w.z = cvt_pk_bf16(b[0], b[1]); w.w = cvt_pk_bf16(b[2], b[3]); return w; }
;     __device__ __forceinline__ void operator()(f32x4 (&acc)[2][2][4][2], const Unit& u, int wr, int wc, int fr, int fq) const {
;     ...
;                 const int row = row0 + ai * HALF + m * 16; float sq = 0.f;
; #pragma unroll
;                 for (int bj = 0; bj < 2; ++bj) {
;                     const size_t off = (size_t)row * D + col0 + bj * 32;
;                     const u32x4 xw = *(const u32x4*)(xin + off);
;                     const f32x4 v0 = acc[ai][bj][m][0] + (f32x4){bf_lo(xw.x), bf_hi(xw.x), bf_lo(xw.y), bf_hi(xw.y)}, v1 = acc[ai][bj][m][1] + (f32x4){bf_lo(xw.z), bf_hi(xw.z), bf_lo(xw.w), bf_hi(xw.w)};
;                     *(u32x4*)(xb + off) = pack8(v0, v1);
;                     sq += (v0[0] * v0[0] + v0[1] * v0[1]) + (v0[2] * v0[2] + v0[3] * v0[3]) + (v1[0] * v1[0] + v1[1] * v1[1]) + (v1[2] * v1[2] + v1[3] * v1[3]);
	v_lshlrev_b32_e32 v246, 16, v198
	v_and_b32_e32 v247, 0xffff0000, v198
	v_lshlrev_b32_e32 v248, 16, v199
	v_and_b32_e32 v249, 0xffff0000, v199
	v_pk_add_f32 v[78:79], v[78:79], v[246:247]
	v_pk_add_f32 v[80:81], v[80:81], v[248:249]
	v_lshlrev_b32_e32 v246, 16, v200
	v_and_b32_e32 v247, 0xffff0000, v200
	v_lshlrev_b32_e32 v248, 16, v201
	v_and_b32_e32 v249, 0xffff0000, v201
	v_pk_add_f32 v[74:75], v[74:75], v[246:247]
	v_pk_add_f32 v[76:77], v[76:77], v[248:249]
	v_cvt_pk_bf16_f32 v198, v78, v79
	v_cvt_pk_bf16_f32 v199, v80, v81
	v_cvt_pk_bf16_f32 v200, v74, v75
	v_cvt_pk_bf16_f32 v201, v76, v77
	global_store_dwordx4 v153, v[198:201], s[44:45]
	v_pk_mul_f32 v[250:251], v[78:79], v[78:79]
	v_pk_fma_f32 v[250:251], v[80:81], v[80:81], v[250:251]
	v_pk_fma_f32 v[250:251], v[74:75], v[74:75], v[250:251]
	v_pk_fma_f32 v[250:251], v[76:77], v[76:77], v[250:251]
	s_waitcnt vmcnt(15)
	v_lshlrev_b32_e32 v246, 16, v202
	v_and_b32_e32 v247, 0xffff0000, v202
	v_lshlrev_b32_e32 v248, 16, v203
	v_and_b32_e32 v249, 0xffff0000, v203
	v_pk_add_f32 v[70:71], v[70:71], v[246:247]
	v_pk_add_f32 v[72:73], v[72:73], v[248:249]
	v_lshlrev_b32_e32 v246, 16, v204
	v_and_b32_e32 v247, 0xffff0000, v204
	v_lshlrev_b32_e32 v248, 16, v205
	v_and_b32_e32 v249, 0xffff0000, v205
	v_pk_add_f32 v[66:67], v[66:67], v[246:247]
	v_pk_add_f32 v[68:69], v[68:69], v[248:249]
	v_cvt_pk_bf16_f32 v202, v70, v71
	v_cvt_pk_bf16_f32 v203, v72, v73
	v_cvt_pk_bf16_f32 v204, v66, v67
	v_cvt_pk_bf16_f32 v205, v68, v69
	global_store_dwordx4 v153, v[202:205], s[44:45] offset:64
	v_pk_fma_f32 v[250:251], v[70:71], v[70:71], v[250:251]
	v_pk_fma_f32 v[250:251], v[72:73], v[72:73], v[250:251]
	v_pk_fma_f32 v[250:251], v[66:67], v[66:67], v[250:251]
	v_pk_fma_f32 v[250:251], v[68:69], v[68:69], v[250:251]
	v_add_f32_e32 v143, v250, v251
	s_waitcnt vmcnt(15)
	v_lshlrev_b32_e32 v246, 16, v206
	v_and_b32_e32 v247, 0xffff0000, v206
	v_lshlrev_b32_e32 v248, 16, v207
	v_and_b32_e32 v249, 0xffff0000, v207
	v_pk_add_f32 v[62:63], v[62:63], v[246:247]
	v_pk_add_f32 v[64:65], v[64:65], v[248:249]
	v_lshlrev_b32_e32 v246, 16, v208
	v_and_b32_e32 v247, 0xffff0000, v208
	v_lshlrev_b32_e32 v248, 16, v209
	v_and_b32_e32 v249, 0xffff0000, v209
	v_pk_add_f32 v[58:59], v[58:59], v[246:247]
	v_pk_add_f32 v[60:61], v[60:61], v[248:249]
	v_cvt_pk_bf16_f32 v206, v62, v63
	v_cvt_pk_bf16_f32 v207, v64, v65
	v_cvt_pk_bf16_f32 v208, v58, v59
	v_cvt_pk_bf16_f32 v209, v60, v61
	global_store_dwordx4 v154, v[206:209], s[44:45]
	v_pk_mul_f32 v[250:251], v[62:63], v[62:63]
	v_pk_fma_f32 v[250:251], v[64:65], v[64:65], v[250:251]
	v_pk_fma_f32 v[250:251], v[58:59], v[58:59], v[250:251]
	v_pk_fma_f32 v[250:251], v[60:61], v[60:61], v[250:251]
	s_waitcnt vmcnt(15)
	v_lshlrev_b32_e32 v246, 16, v210
	v_and_b32_e32 v247, 0xffff0000, v210
	v_lshlrev_b32_e32 v248, 16, v211
	v_and_b32_e32 v249, 0xffff0000, v211
	v_pk_add_f32 v[54:55], v[54:55], v[246:247]
	v_pk_add_f32 v[56:57], v[56:57], v[248:249]
	v_lshlrev_b32_e32 v246, 16, v212
	v_and_b32_e32 v247, 0xffff0000, v212
	v_lshlrev_b32_e32 v248, 16, v213
	v_and_b32_e32 v249, 0xffff0000, v213
	v_pk_add_f32 v[50:51], v[50:51], v[246:247]
	v_pk_add_f32 v[52:53], v[52:53], v[248:249]
	v_cvt_pk_bf16_f32 v210, v54, v55
	v_cvt_pk_bf16_f32 v211, v56, v57
	v_cvt_pk_bf16_f32 v212, v50, v51
	v_cvt_pk_bf16_f32 v213, v52, v53
	global_store_dwordx4 v154, v[210:213], s[44:45] offset:64
	v_pk_fma_f32 v[250:251], v[54:55], v[54:55], v[250:251]
	v_pk_fma_f32 v[250:251], v[56:57], v[56:57], v[250:251]
	v_pk_fma_f32 v[250:251], v[50:51], v[50:51], v[250:251]
	v_pk_fma_f32 v[250:251], v[52:53], v[52:53], v[250:251]
	v_add_f32_e32 v144, v250, v251
	s_waitcnt vmcnt(15)
	v_lshlrev_b32_e32 v246, 16, v214
	v_and_b32_e32 v247, 0xffff0000, v214
	v_lshlrev_b32_e32 v248, 16, v215
	v_and_b32_e32 v249, 0xffff0000, v215
	v_pk_add_f32 v[46:47], v[46:47], v[246:247]
	v_pk_add_f32 v[48:49], v[48:49], v[248:249]
	v_lshlrev_b32_e32 v246, 16, v216
	v_and_b32_e32 v247, 0xffff0000, v216
	v_lshlrev_b32_e32 v248, 16, v217
	v_and_b32_e32 v249, 0xffff0000, v217
	v_pk_add_f32 v[42:43], v[42:43], v[246:247]
	v_pk_add_f32 v[44:45], v[44:45], v[248:249]
	v_cvt_pk_bf16_f32 v214, v46, v47
	v_cvt_pk_bf16_f32 v215, v48, v49
	v_cvt_pk_bf16_f32 v216, v42, v43
	v_cvt_pk_bf16_f32 v217, v44, v45
	global_store_dwordx4 v155, v[214:217], s[44:45]
	v_pk_mul_f32 v[250:251], v[46:47], v[46:47]
	v_pk_fma_f32 v[250:251], v[48:49], v[48:49], v[250:251]
	v_pk_fma_f32 v[250:251], v[42:43], v[42:43], v[250:251]
	v_pk_fma_f32 v[250:251], v[44:45], v[44:45], v[250:251]
	s_waitcnt vmcnt(15)
	v_lshlrev_b32_e32 v246, 16, v218
	v_and_b32_e32 v247, 0xffff0000, v218
	v_lshlrev_b32_e32 v248, 16, v219
	v_and_b32_e32 v249, 0xffff0000, v219
	v_pk_add_f32 v[38:39], v[38:39], v[246:247]
	v_pk_add_f32 v[40:41], v[40:41], v[248:249]
	v_lshlrev_b32_e32 v246, 16, v220
	v_and_b32_e32 v247, 0xffff0000, v220
	v_lshlrev_b32_e32 v248, 16, v221
	v_and_b32_e32 v249, 0xffff0000, v221
	v_pk_add_f32 v[34:35], v[34:35], v[246:247]
	v_pk_add_f32 v[36:37], v[36:37], v[248:249]
	v_cvt_pk_bf16_f32 v218, v38, v39
	v_cvt_pk_bf16_f32 v219, v40, v41
	v_cvt_pk_bf16_f32 v220, v34, v35
	v_cvt_pk_bf16_f32 v221, v36, v37
	global_store_dwordx4 v155, v[218:221], s[44:45] offset:64
	v_pk_fma_f32 v[250:251], v[38:39], v[38:39], v[250:251]
	v_pk_fma_f32 v[250:251], v[40:41], v[40:41], v[250:251]
	v_pk_fma_f32 v[250:251], v[34:35], v[34:35], v[250:251]
	v_pk_fma_f32 v[250:251], v[36:37], v[36:37], v[250:251]
	v_add_f32_e32 v145, v250, v251
	s_waitcnt vmcnt(15)
; __device__ __forceinline__ float bf_lo(unsigned w) { return __uint_as_float(w << 16); }
; __device__ __forceinline__ float bf_hi(unsigned w) { return __uint_as_float(w & 0xffff0000u); }
; __device__ __forceinline__ u32x4 pack8(f32x4 a, f32x4 b) { u32x4 w; w.x = cvt_pk_bf16(a[0], a[1]); w.y = cvt_pk_bf16(a[2], a[3]); w.z = cvt_pk_bf16(b[0], b[1]); w.w = cvt_pk_bf16(b[2], b[3]); return w; }
; #define PG8_BAR __builtin_amdgcn_s_barrier()
; template <class Epi, class SchedT, bool ALIGN_EPI, bool SP2>
; __device__ __forceinline__ void gemm_phase(LAS unsigned char* lds, const int ldk, const int nt, const SchedT& S, const Epi& E) {
;     ...
;         if (!has_next) break;
;         if (!(SchedT::kMode == 2 && cur.kind == 0)) {
; #pragma unroll
;         for (int a = 0; a < 2; ++a)
; #pragma unroll
;             for (int b = 0; b < 2; ++b)
; #pragma unroll
;                 for (int m = 0; m < 4; ++m)
; #pragma unroll
;                     for (int n = 0; n < 2; ++n) acc[a][b][m][n] = (f32x4){0.f, 0.f, 0.f, 0.f};
;         }
;         cur = nxt; cA = nA; cB = nB; ++ui;
;         if constexpr (ALIGN_EPI) { if (wr == 1) PG8_BAR; }
;     __device__ __forceinline__ void operator()(f32x4 (&acc)[2][2][4][2], const Unit& u, int wr, int wc, int fr, int fq) const {
;     ...
;                 const int row = row0 + ai * HALF + m * 16; float sq = 0.f;
; #pragma unroll
;                 for (int bj = 0; bj < 2; ++bj) {
;                     const size_t off = (size_t)row * D + col0 + bj * 32;
;                     const u32x4 xw = *(const u32x4*)(xin + off);
;                     const f32x4 v0 = acc[ai][bj][m][0] + (f32x4){bf_lo(xw.x), bf_hi(xw.x), bf_lo(xw.y), bf_hi(xw.y)}, v1 = acc[ai][bj][m][1] + (f32x4){bf_lo(xw.z), bf_hi(xw.z), bf_lo(xw.w), bf_hi(xw.w)};
;                     *(u32x4*)(xb + off) = pack8(v0, v1);
;                     sq += (v0[0] * v0[0] + v0[1] * v0[1]) + (v0[2] * v0[2] + v0[3] * v0[3]) + (v1[0] * v1[0] + v1[1] * v1[1]) + (v1[2] * v1[2] + v1[3] * v1[3]);
;                 }
;                 sq += __shfl_xor(sq, 16); sq += __shfl_xor(sq, 32);
;                 if (fq == 0) ss[(size_t)row * 32 + u.pn * 4 + wc] = sq;
	v_lshlrev_b32_e32 v246, 16, v222
	v_and_b32_e32 v247, 0xffff0000, v222
	v_lshlrev_b32_e32 v248, 16, v223
	v_and_b32_e32 v249, 0xffff0000, v223
	v_pk_add_f32 v[30:31], v[30:31], v[246:247]
	v_pk_add_f32 v[32:33], v[32:33], v[248:249]
	v_lshlrev_b32_e32 v246, 16, v224
	v_and_b32_e32 v247, 0xffff0000, v224
	v_lshlrev_b32_e32 v248, 16, v225
	v_and_b32_e32 v249, 0xffff0000, v225
	v_pk_add_f32 v[26:27], v[26:27], v[246:247]
	v_pk_add_f32 v[28:29], v[28:29], v[248:249]
	v_cvt_pk_bf16_f32 v222, v30, v31
	v_cvt_pk_bf16_f32 v223, v32, v33
	v_cvt_pk_bf16_f32 v224, v26, v27
	v_cvt_pk_bf16_f32 v225, v28, v29
	global_store_dwordx4 v156, v[222:225], s[44:45]
	v_pk_mul_f32 v[250:251], v[30:31], v[30:31]
	v_pk_fma_f32 v[250:251], v[32:33], v[32:33], v[250:251]
	v_pk_fma_f32 v[250:251], v[26:27], v[26:27], v[250:251]
	v_pk_fma_f32 v[250:251], v[28:29], v[28:29], v[250:251]
	s_waitcnt vmcnt(15)
	v_lshlrev_b32_e32 v246, 16, v226
	v_and_b32_e32 v247, 0xffff0000, v226
	v_lshlrev_b32_e32 v248, 16, v227
	v_and_b32_e32 v249, 0xffff0000, v227
	v_pk_add_f32 v[22:23], v[22:23], v[246:247]
	v_pk_add_f32 v[24:25], v[24:25], v[248:249]
	v_lshlrev_b32_e32 v246, 16, v228
	v_and_b32_e32 v247, 0xffff0000, v228
	v_lshlrev_b32_e32 v248, 16, v229
	v_and_b32_e32 v249, 0xffff0000, v229
	v_pk_add_f32 v[18:19], v[18:19], v[246:247]
	v_pk_add_f32 v[20:21], v[20:21], v[248:249]
	v_cvt_pk_bf16_f32 v226, v22, v23
	v_cvt_pk_bf16_f32 v227, v24, v25
	v_cvt_pk_bf16_f32 v228, v18, v19
	v_cvt_pk_bf16_f32 v229, v20, v21
	global_store_dwordx4 v156, v[226:229], s[44:45] offset:64
	v_pk_fma_f32 v[250:251], v[22:23], v[22:23], v[250:251]
	v_pk_fma_f32 v[250:251], v[24:25], v[24:25], v[250:251]
	v_pk_fma_f32 v[250:251], v[18:19], v[18:19], v[250:251]
	v_pk_fma_f32 v[250:251], v[20:21], v[20:21], v[250:251]
	v_add_f32_e32 v162, v250, v251
	s_waitcnt vmcnt(15)
	v_lshlrev_b32_e32 v246, 16, v230
	v_and_b32_e32 v247, 0xffff0000, v230
	v_lshlrev_b32_e32 v248, 16, v231
	v_and_b32_e32 v249, 0xffff0000, v231
	v_pk_add_f32 v[14:15], v[14:15], v[246:247]
	v_pk_add_f32 v[16:17], v[16:17], v[248:249]
	v_lshlrev_b32_e32 v246, 16, v232
	v_and_b32_e32 v247, 0xffff0000, v232
	v_lshlrev_b32_e32 v248, 16, v233
	v_and_b32_e32 v249, 0xffff0000, v233
	v_pk_add_f32 v[10:11], v[10:11], v[246:247]
	v_pk_add_f32 v[12:13], v[12:13], v[248:249]
	v_cvt_pk_bf16_f32 v230, v14, v15
	v_cvt_pk_bf16_f32 v231, v16, v17
	v_cvt_pk_bf16_f32 v232, v10, v11
	v_cvt_pk_bf16_f32 v233, v12, v13
	global_store_dwordx4 v157, v[230:233], s[44:45]
	v_pk_mul_f32 v[250:251], v[14:15], v[14:15]
	v_pk_fma_f32 v[250:251], v[16:17], v[16:17], v[250:251]
	v_pk_fma_f32 v[250:251], v[10:11], v[10:11], v[250:251]
	v_pk_fma_f32 v[250:251], v[12:13], v[12:13], v[250:251]
	s_waitcnt vmcnt(15)
	v_lshlrev_b32_e32 v246, 16, v234
	v_and_b32_e32 v247, 0xffff0000, v234
	v_lshlrev_b32_e32 v248, 16, v235
	v_and_b32_e32 v249, 0xffff0000, v235
	v_pk_add_f32 v[6:7], v[6:7], v[246:247]
	v_pk_add_f32 v[8:9], v[8:9], v[248:249]
	v_lshlrev_b32_e32 v246, 16, v236
	v_and_b32_e32 v247, 0xffff0000, v236
	v_lshlrev_b32_e32 v248, 16, v237
	v_and_b32_e32 v249, 0xffff0000, v237
	v_pk_add_f32 v[2:3], v[2:3], v[246:247]
	v_pk_add_f32 v[4:5], v[4:5], v[248:249]
	v_cvt_pk_bf16_f32 v234, v6, v7
	v_cvt_pk_bf16_f32 v235, v8, v9
	v_cvt_pk_bf16_f32 v236, v2, v3
	v_cvt_pk_bf16_f32 v237, v4, v5
	global_store_dwordx4 v157, v[234:237], s[44:45] offset:64
	v_pk_fma_f32 v[250:251], v[6:7], v[6:7], v[250:251]
	v_pk_fma_f32 v[250:251], v[8:9], v[8:9], v[250:251]
	v_pk_fma_f32 v[250:251], v[2:3], v[2:3], v[250:251]
	v_pk_fma_f32 v[250:251], v[4:5], v[4:5], v[250:251]
	v_add_f32_e32 v238, v250, v251
	ds_bpermute_b32 v174, v239, v140
	ds_bpermute_b32 v175, v239, v141
	ds_bpermute_b32 v176, v239, v142
	ds_bpermute_b32 v177, v239, v143
	ds_bpermute_b32 v178, v239, v144
	ds_bpermute_b32 v179, v239, v145
	ds_bpermute_b32 v180, v239, v162
	ds_bpermute_b32 v181, v239, v238
	s_waitcnt lgkmcnt(0)
	v_add_f32_e32 v140, v140, v174
	v_add_f32_e32 v141, v141, v175
	v_add_f32_e32 v142, v142, v176
	v_add_f32_e32 v143, v143, v177
	v_add_f32_e32 v144, v144, v178
	v_add_f32_e32 v145, v145, v179
	v_add_f32_e32 v162, v162, v180
	v_add_f32_e32 v238, v238, v181
	ds_bpermute_b32 v174, v252, v140
	ds_bpermute_b32 v175, v252, v141
	ds_bpermute_b32 v176, v252, v142
	ds_bpermute_b32 v177, v252, v143
	ds_bpermute_b32 v178, v252, v144
	ds_bpermute_b32 v179, v252, v145
	ds_bpermute_b32 v180, v252, v162
	ds_bpermute_b32 v181, v252, v238
	s_waitcnt lgkmcnt(0)
	v_add_f32_e32 v140, v140, v174
	v_add_f32_e32 v141, v141, v175
	v_add_f32_e32 v142, v142, v176
	v_add_f32_e32 v143, v143, v177
	v_add_f32_e32 v144, v144, v178
	v_add_f32_e32 v145, v145, v179
	v_add_f32_e32 v162, v162, v180
	v_add_f32_e32 v238, v238, v181
	s_and_saveexec_b64 s[12:13], s[38:39]
	global_store_dword v158, v140, s[46:47]
	global_store_dword v158, v141, s[46:47] offset:2048
	global_store_dword v159, v142, s[46:47]
	global_store_dword v159, v143, s[46:47] offset:2048
	global_store_dword v160, v144, s[46:47]
	global_store_dword v160, v145, s[46:47] offset:2048
	global_store_dword v161, v162, s[46:47]
	global_store_dword v161, v238, s[46:47] offset:2048
	s_mov_b32 s86, 0x20000
	s_mov_b32 s87, 0x28000
	s_or_b64 exec, exec, s[12:13]
	s_and_b64 vcc, exec, s[40:41]
	s_mov_b64 s[12:13], -1
	s_cbranch_vccnz .LBB0_662
	s_setprio 0
	s_andn2_b64 vcc, exec, s[18:19]
	s_cbranch_vccnz .LBB0_661
	s_barrier
	s_setprio 1
	s_branch .LBB0_661

; #define PG8_STAGE(bufoff, gbase, voff) do { _Pragma("unroll") for (int _i = 0; _i < 2; ++_i) \
;         __builtin_amdgcn_global_load_lds((const __attribute__((address_space(1))) unsigned*)((const char*)(gbase) + (voff)[_i]), (LAS unsigned*)(lds + (bufoff) + ldsw + _i * 8192), 16, 0, 0); } while (0)
; #define PG8_LDA(dst, b, h) do { _Pragma("unroll") for (int m = 0; m < 4; ++m) _Pragma("unroll") for (int k = 0; k < 2; ++k) dst[m][k] = *(const LAS bf16x8*)(lds + PG8_SA(b, h) + aoff + m * 2048 + k * 1024); } while (0)
; #define PG8_LDB(dst, b, h) do { _Pragma("unroll") for (int n = 0; n < 2; ++n) _Pragma("unroll") for (int k = 0; k < 2; ++k) dst[n][k] = *(const LAS bf16x8*)(lds + PG8_SB(b, h) + boff + n * 2048 + k * 1024); } while (0)
; #define PG8_MMA(ai, bj, At, Bt) do { __builtin_amdgcn_s_setprio(1); _Pragma("unroll") for (int m = 0; m < 4; ++m) _Pragma("unroll") for (int n = 0; n < 2; ++n) _Pragma("unroll") for (int k = 0; k < 2; ++k) \
;         acc[ai][bj][m][n] = __builtin_amdgcn_mfma_f32_16x16x32_bf16(Bt[n][k], At[m][k], acc[ai][bj][m][n], 0, 0, 0); __builtin_amdgcn_s_setprio(0); } while (0)
; #define PG8_WAIT_V(n) asm volatile("s_waitcnt vmcnt(" #n ")" ::: "memory")
; #define PG8_WAIT_L(n) asm volatile("s_waitcnt lgkmcnt(" #n ")" ::: "memory")
; #define PG8_BAR __builtin_amdgcn_s_barrier()
; template <class Epi, class SchedT, bool ALIGN_EPI, bool SP2>
; __device__ __forceinline__ void gemm_phase(LAS unsigned char* lds, const int ldk, const int nt, const SchedT& S, const Epi& E) {
;     ...
;             const bool last = (t == nt - 2);
;             const char* a1 = cA + (size_t)(t + 1) * kstep;
;             const char* a2 = last ? nA : cA + (size_t)(t + 2) * kstep; const char* b2 = last ? nB : cB + (size_t)(t + 2) * kstep;
;             const char* a3 = a2 + kstep; const char* b3 = b2 + kstep;
;             if constexpr (SP2) {
;             PG8_LDB(B0, 0, 0); PG8_LDB(B1, 0, 1); PG8_SCHED; PG8_LDA(At, 0, 0); PG8_STAGE(PG8_SA(1, 1), a1 + hstep, voffA);
;             PG8_WAIT_V(8); PG8_WAIT_L(0); PG8_BAR; PG8_MMA(0, 0, At, B0); PG8_MMA(0, 1, At, B1); PG8_BAR; PG8_SCHED;
;             PG8_LDA(At, 0, 1); PG8_STAGE(PG8_SB(0, 0), b2, voffB); PG8_STAGE(PG8_SB(0, 1), b2 + hstepB, voffB); PG8_STAGE(PG8_SA(0, 0), a2, voffA);
;             PG8_WAIT_V(8); PG8_WAIT_L(0); PG8_BAR; PG8_MMA(1, 0, At, B0); PG8_MMA(1, 1, At, B1); PG8_BAR; PG8_SCHED;
.LBB0_948:
	s_add_u32 s16, s12, 0x100
	s_addc_u32 s17, s13, 0
	s_add_i32 s64, 0, 0x10000
	s_cmpk_eq_i32 s83, 0x52
	s_cselect_b32 s47, s1, s17
	s_cselect_b32 s46, s0, s16
	v_add_u32_e32 v144, s64, v147
	s_cselect_b32 s45, s43, s82
	s_cselect_b32 s44, s42, s81
	s_add_i32 s65, 0, 0x14000
	ds_read_b128 v[140:143], v144
	ds_read_b128 v[150:153], v144 offset:1024
	ds_read_b128 v[154:157], v144 offset:2048
	ds_read_b128 v[158:161], v144 offset:3072
	v_add_u32_e32 v144, s65, v147
	ds_read_b128 v[174:177], v144
	ds_read_b128 v[178:181], v144 offset:1024
	ds_read_b128 v[182:185], v144 offset:2048
	ds_read_b128 v[186:189], v144 offset:3072
	v_lshl_add_u64 v[144:145], s[12:13], 0, v[136:137]
	s_add_i32 m0, s53, 0xc000
	ds_read_b128 v[190:193], v149
	ds_read_b128 v[194:197], v149 offset:1024
	ds_read_b128 v[198:201], v149 offset:2048
	ds_read_b128 v[202:205], v149 offset:3072
	ds_read_b128 v[206:209], v149 offset:4096
	ds_read_b128 v[210:213], v149 offset:5120
	ds_read_b128 v[214:217], v149 offset:6144
	ds_read_b128 v[218:221], v149 offset:7168
	global_load_lds_dwordx4 v[144:145], off
	v_lshl_add_u64 v[144:145], s[12:13], 0, v[138:139]
	s_add_i32 m0, s53, 0xe000
	s_nop 0
	global_load_lds_dwordx4 v[144:145], off
	s_waitcnt vmcnt(8)
	s_waitcnt lgkmcnt(0)
	s_barrier
	s_waitcnt lgkmcnt(0)
	v_mfma_f32_16x16x32_bf16 v[126:129], v[140:143], v[190:193], v[126:129]
	v_mfma_f32_16x16x32_bf16 v[122:125], v[154:157], v[190:193], v[122:125]
	v_mfma_f32_16x16x32_bf16 v[110:113], v[140:143], v[198:201], v[110:113]
	v_mfma_f32_16x16x32_bf16 v[106:109], v[154:157], v[198:201], v[106:109]
	v_mfma_f32_16x16x32_bf16 v[94:97], v[140:143], v[206:209], v[94:97]
	v_mfma_f32_16x16x32_bf16 v[90:93], v[154:157], v[206:209], v[90:93]
	v_mfma_f32_16x16x32_bf16 v[78:81], v[140:143], v[214:217], v[78:81]
	v_mfma_f32_16x16x32_bf16 v[74:77], v[154:157], v[214:217], v[74:77]
	v_mfma_f32_16x16x32_bf16 v[126:129], v[150:153], v[194:197], v[126:129]
	v_mfma_f32_16x16x32_bf16 v[122:125], v[158:161], v[194:197], v[122:125]
	v_mfma_f32_16x16x32_bf16 v[110:113], v[150:153], v[202:205], v[110:113]
	v_mfma_f32_16x16x32_bf16 v[106:109], v[158:161], v[202:205], v[106:109]
	v_mfma_f32_16x16x32_bf16 v[94:97], v[150:153], v[210:213], v[94:97]
	v_mfma_f32_16x16x32_bf16 v[90:93], v[158:161], v[210:213], v[90:93]
	v_mfma_f32_16x16x32_bf16 v[78:81], v[150:153], v[218:221], v[78:81]
	v_mfma_f32_16x16x32_bf16 v[74:77], v[158:161], v[218:221], v[74:77]
	v_mfma_f32_16x16x32_bf16 v[118:121], v[174:177], v[190:193], v[118:121]
	v_mfma_f32_16x16x32_bf16 v[114:117], v[182:185], v[190:193], v[114:117]
	v_mfma_f32_16x16x32_bf16 v[102:105], v[174:177], v[198:201], v[102:105]
	v_mfma_f32_16x16x32_bf16 v[98:101], v[182:185], v[198:201], v[98:101]
	v_mfma_f32_16x16x32_bf16 v[86:89], v[174:177], v[206:209], v[86:89]
	v_mfma_f32_16x16x32_bf16 v[82:85], v[182:185], v[206:209], v[82:85]
	v_mfma_f32_16x16x32_bf16 v[70:73], v[174:177], v[214:217], v[70:73]
	v_mfma_f32_16x16x32_bf16 v[66:69], v[182:185], v[214:217], v[66:69]
	v_mfma_f32_16x16x32_bf16 v[118:121], v[178:181], v[194:197], v[118:121]
	v_mfma_f32_16x16x32_bf16 v[114:117], v[186:189], v[194:197], v[114:117]
	v_mfma_f32_16x16x32_bf16 v[102:105], v[178:181], v[202:205], v[102:105]
	v_mfma_f32_16x16x32_bf16 v[98:101], v[186:189], v[202:205], v[98:101]
	v_mfma_f32_16x16x32_bf16 v[86:89], v[178:181], v[210:213], v[86:89]
	v_mfma_f32_16x16x32_bf16 v[82:85], v[186:189], v[210:213], v[82:85]
	v_mfma_f32_16x16x32_bf16 v[70:73], v[178:181], v[218:221], v[70:73]
	v_mfma_f32_16x16x32_bf16 v[66:69], v[186:189], v[218:221], v[66:69]
	s_barrier
	s_add_i32 s12, s64, s52
	v_lshl_add_u64 v[144:145], s[44:45], 0, v[0:1]
	s_mov_b32 m0, s12
	ds_read_b128 v[190:193], v149 offset:16384
	ds_read_b128 v[194:197], v149 offset:17408
	ds_read_b128 v[198:201], v149 offset:18432
	ds_read_b128 v[202:205], v149 offset:19456
	ds_read_b128 v[206:209], v149 offset:20480
	ds_read_b128 v[210:213], v149 offset:21504
	ds_read_b128 v[214:217], v149 offset:22528
	ds_read_b128 v[218:221], v149 offset:23552
	global_load_lds_dwordx4 v[144:145], off
	s_add_i32 m0, s12, 0x2000
	s_add_u32 s12, s44, 0x56000
	v_lshl_add_u64 v[222:223], s[44:45], 0, v[134:135]
	s_addc_u32 s13, s45, 0
	s_add_i32 s64, s65, s52
	global_load_lds_dwordx4 v[222:223], off
	v_lshl_add_u64 v[224:225], s[12:13], 0, v[0:1]
	s_mov_b32 m0, s64
	v_lshl_add_u64 v[226:227], s[46:47], 0, v[132:133]
	global_load_lds_dwordx4 v[224:225], off
	v_lshl_add_u64 v[224:225], s[12:13], 0, v[134:135]
	s_add_i32 m0, s64, 0x2000
	s_nop 0
	global_load_lds_dwordx4 v[224:225], off
	v_lshl_add_u64 v[224:225], s[46:47], 0, v[130:131]
	s_mov_b32 m0, s53
	s_nop 0
	global_load_lds_dwordx4 v[224:225], off
	s_mov_b32 m0, s54
	s_nop 0
	global_load_lds_dwordx4 v[226:227], off
	s_waitcnt vmcnt(8)
	s_waitcnt lgkmcnt(0)
	s_barrier
; #define PG8_STAGE(bufoff, gbase, voff) do { _Pragma("unroll") for (int _i = 0; _i < 2; ++_i) \
;         __builtin_amdgcn_global_load_lds((const __attribute__((address_space(1))) unsigned*)((const char*)(gbase) + (voff)[_i]), (LAS unsigned*)(lds + (bufoff) + ldsw + _i * 8192), 16, 0, 0); } while (0)
; #define PG8_LDA(dst, b, h) do { _Pragma("unroll") for (int m = 0; m < 4; ++m) _Pragma("unroll") for (int k = 0; k < 2; ++k) dst[m][k] = *(const LAS bf16x8*)(lds + PG8_SA(b, h) + aoff + m * 2048 + k * 1024); } while (0)
; #define PG8_LDB(dst, b, h) do { _Pragma("unroll") for (int n = 0; n < 2; ++n) _Pragma("unroll") for (int k = 0; k < 2; ++k) dst[n][k] = *(const LAS bf16x8*)(lds + PG8_SB(b, h) + boff + n * 2048 + k * 1024); } while (0)
; #define PG8_MMA(ai, bj, At, Bt) do { __builtin_amdgcn_s_setprio(1); _Pragma("unroll") for (int m = 0; m < 4; ++m) _Pragma("unroll") for (int n = 0; n < 2; ++n) _Pragma("unroll") for (int k = 0; k < 2; ++k) \
;         acc[ai][bj][m][n] = __builtin_amdgcn_mfma_f32_16x16x32_bf16(Bt[n][k], At[m][k], acc[ai][bj][m][n], 0, 0, 0); __builtin_amdgcn_s_setprio(0); } while (0)
; #define PG8_WAIT_V(n) asm volatile("s_waitcnt vmcnt(" #n ")" ::: "memory")
; #define PG8_WAIT_L(n) asm volatile("s_waitcnt lgkmcnt(" #n ")" ::: "memory")
; #define PG8_BAR __builtin_amdgcn_s_barrier()
; #define PG8_SCHED __builtin_amdgcn_sched_barrier(0)
; template <class Epi, class SchedT, bool ALIGN_EPI, bool SP2>
; __device__ __forceinline__ void gemm_phase(LAS unsigned char* lds, const int ldk, const int nt, const SchedT& S, const Epi& E) {
;     ...
;             PG8_WAIT_V(8); PG8_WAIT_L(0); PG8_BAR; PG8_MMA(1, 0, At, B0); PG8_MMA(1, 1, At, B1); PG8_BAR; PG8_SCHED;
;             PG8_LDB(B0, 1, 0); PG8_LDB(B1, 1, 1); PG8_SCHED; PG8_LDA(At, 1, 0); PG8_STAGE(PG8_SA(0, 1), a2 + hstep, voffA);
;             PG8_WAIT_V(8); PG8_WAIT_L(0); PG8_BAR; PG8_MMA(0, 0, At, B0); PG8_MMA(0, 1, At, B1); PG8_BAR; PG8_SCHED;
	s_waitcnt lgkmcnt(0)
	v_mfma_f32_16x16x32_bf16 v[62:65], v[140:143], v[190:193], v[62:65]
	v_mfma_f32_16x16x32_bf16 v[58:61], v[154:157], v[190:193], v[58:61]
	v_mfma_f32_16x16x32_bf16 v[46:49], v[140:143], v[198:201], v[46:49]
	v_mfma_f32_16x16x32_bf16 v[42:45], v[154:157], v[198:201], v[42:45]
	v_mfma_f32_16x16x32_bf16 v[30:33], v[140:143], v[206:209], v[30:33]
	v_mfma_f32_16x16x32_bf16 v[26:29], v[154:157], v[206:209], v[26:29]
	v_mfma_f32_16x16x32_bf16 v[14:17], v[140:143], v[214:217], v[14:17]
	v_mfma_f32_16x16x32_bf16 v[10:13], v[154:157], v[214:217], v[10:13]
	v_mfma_f32_16x16x32_bf16 v[62:65], v[150:153], v[194:197], v[62:65]
	v_mfma_f32_16x16x32_bf16 v[58:61], v[158:161], v[194:197], v[58:61]
	v_mfma_f32_16x16x32_bf16 v[46:49], v[150:153], v[202:205], v[46:49]
	v_mfma_f32_16x16x32_bf16 v[42:45], v[158:161], v[202:205], v[42:45]
	v_mfma_f32_16x16x32_bf16 v[30:33], v[150:153], v[210:213], v[30:33]
	v_mfma_f32_16x16x32_bf16 v[26:29], v[158:161], v[210:213], v[26:29]
	v_mfma_f32_16x16x32_bf16 v[14:17], v[150:153], v[218:221], v[14:17]
	v_mfma_f32_16x16x32_bf16 v[10:13], v[158:161], v[218:221], v[10:13]
	v_mfma_f32_16x16x32_bf16 v[54:57], v[174:177], v[190:193], v[54:57]
	v_mfma_f32_16x16x32_bf16 v[50:53], v[182:185], v[190:193], v[50:53]
	v_mfma_f32_16x16x32_bf16 v[38:41], v[174:177], v[198:201], v[38:41]
	v_mfma_f32_16x16x32_bf16 v[34:37], v[182:185], v[198:201], v[34:37]
	v_mfma_f32_16x16x32_bf16 v[22:25], v[174:177], v[206:209], v[22:25]
	v_mfma_f32_16x16x32_bf16 v[18:21], v[182:185], v[206:209], v[18:21]
	v_mfma_f32_16x16x32_bf16 v[6:9], v[174:177], v[214:217], v[6:9]
	v_mfma_f32_16x16x32_bf16 v[2:5], v[182:185], v[214:217], v[2:5]
	v_mfma_f32_16x16x32_bf16 v[54:57], v[178:181], v[194:197], v[54:57]
	v_mfma_f32_16x16x32_bf16 v[50:53], v[186:189], v[194:197], v[50:53]
	v_mfma_f32_16x16x32_bf16 v[38:41], v[178:181], v[202:205], v[38:41]
	v_mfma_f32_16x16x32_bf16 v[34:37], v[186:189], v[202:205], v[34:37]
	v_mfma_f32_16x16x32_bf16 v[22:25], v[178:181], v[210:213], v[22:25]
	v_mfma_f32_16x16x32_bf16 v[18:21], v[186:189], v[210:213], v[18:21]
	v_mfma_f32_16x16x32_bf16 v[6:9], v[178:181], v[218:221], v[6:9]
	v_mfma_f32_16x16x32_bf16 v[2:5], v[186:189], v[218:221], v[2:5]
	s_barrier
	s_add_i32 s64, 0, 0x18000
	s_add_i32 s65, 0, 0x1c000
	v_add_u32_e32 v158, s64, v147
	v_add_u32_e32 v186, s65, v147
	ds_read_b128 v[140:143], v158
	ds_read_b128 v[150:153], v158 offset:1024
	ds_read_b128 v[154:157], v158 offset:2048
	ds_read_b128 v[158:161], v158 offset:3072
	ds_read_b128 v[174:177], v186
	ds_read_b128 v[178:181], v186 offset:1024
	ds_read_b128 v[182:185], v186 offset:2048
	ds_read_b128 v[186:189], v186 offset:3072
	s_add_u32 s12, s46, 0x158000
	s_addc_u32 s13, s47, 0
	s_mov_b32 m0, s55
	v_lshl_add_u64 v[228:229], s[12:13], 0, v[130:131]
	ds_read_b128 v[190:193], v149 offset:32768
	ds_read_b128 v[194:197], v149 offset:33792
	ds_read_b128 v[198:201], v149 offset:34816
	ds_read_b128 v[202:205], v149 offset:35840
	ds_read_b128 v[206:209], v149 offset:36864
	ds_read_b128 v[210:213], v149 offset:37888
	ds_read_b128 v[214:217], v149 offset:38912
	ds_read_b128 v[218:221], v149 offset:39936
	global_load_lds_dwordx4 v[228:229], off
	v_lshl_add_u64 v[228:229], s[12:13], 0, v[132:133]
	s_mov_b32 m0, s56
	s_nop 0
	global_load_lds_dwordx4 v[228:229], off
	s_waitcnt vmcnt(8)
	s_waitcnt lgkmcnt(0)
	s_barrier
	s_waitcnt lgkmcnt(0)
	v_mfma_f32_16x16x32_bf16 v[126:129], v[140:143], v[190:193], v[126:129]
	v_mfma_f32_16x16x32_bf16 v[122:125], v[154:157], v[190:193], v[122:125]
	v_mfma_f32_16x16x32_bf16 v[110:113], v[140:143], v[198:201], v[110:113]
	v_mfma_f32_16x16x32_bf16 v[106:109], v[154:157], v[198:201], v[106:109]
	v_mfma_f32_16x16x32_bf16 v[94:97], v[140:143], v[206:209], v[94:97]
	v_mfma_f32_16x16x32_bf16 v[90:93], v[154:157], v[206:209], v[90:93]
	v_mfma_f32_16x16x32_bf16 v[78:81], v[140:143], v[214:217], v[78:81]
	v_mfma_f32_16x16x32_bf16 v[74:77], v[154:157], v[214:217], v[74:77]
	v_mfma_f32_16x16x32_bf16 v[126:129], v[150:153], v[194:197], v[126:129]
	v_mfma_f32_16x16x32_bf16 v[122:125], v[158:161], v[194:197], v[122:125]
	v_mfma_f32_16x16x32_bf16 v[110:113], v[150:153], v[202:205], v[110:113]
	v_mfma_f32_16x16x32_bf16 v[106:109], v[158:161], v[202:205], v[106:109]
	v_mfma_f32_16x16x32_bf16 v[94:97], v[150:153], v[210:213], v[94:97]
	v_mfma_f32_16x16x32_bf16 v[90:93], v[158:161], v[210:213], v[90:93]
	v_mfma_f32_16x16x32_bf16 v[78:81], v[150:153], v[218:221], v[78:81]
	v_mfma_f32_16x16x32_bf16 v[74:77], v[158:161], v[218:221], v[74:77]
	v_mfma_f32_16x16x32_bf16 v[118:121], v[174:177], v[190:193], v[118:121]
	v_mfma_f32_16x16x32_bf16 v[114:117], v[182:185], v[190:193], v[114:117]
	v_mfma_f32_16x16x32_bf16 v[102:105], v[174:177], v[198:201], v[102:105]
	v_mfma_f32_16x16x32_bf16 v[98:101], v[182:185], v[198:201], v[98:101]
	v_mfma_f32_16x16x32_bf16 v[86:89], v[174:177], v[206:209], v[86:89]
	v_mfma_f32_16x16x32_bf16 v[82:85], v[182:185], v[206:209], v[82:85]
	v_mfma_f32_16x16x32_bf16 v[70:73], v[174:177], v[214:217], v[70:73]
	v_mfma_f32_16x16x32_bf16 v[66:69], v[182:185], v[214:217], v[66:69]
	v_mfma_f32_16x16x32_bf16 v[118:121], v[178:181], v[194:197], v[118:121]
	v_mfma_f32_16x16x32_bf16 v[114:117], v[186:189], v[194:197], v[114:117]
	v_mfma_f32_16x16x32_bf16 v[102:105], v[178:181], v[202:205], v[102:105]
	v_mfma_f32_16x16x32_bf16 v[98:101], v[186:189], v[202:205], v[98:101]
	v_mfma_f32_16x16x32_bf16 v[86:89], v[178:181], v[210:213], v[86:89]
	v_mfma_f32_16x16x32_bf16 v[82:85], v[186:189], v[210:213], v[82:85]
	v_mfma_f32_16x16x32_bf16 v[70:73], v[178:181], v[218:221], v[70:73]
	v_mfma_f32_16x16x32_bf16 v[66:69], v[186:189], v[218:221], v[66:69]
	s_barrier
; #define PG8_STAGE(bufoff, gbase, voff) do { _Pragma("unroll") for (int _i = 0; _i < 2; ++_i) \
;         __builtin_amdgcn_global_load_lds((const __attribute__((address_space(1))) unsigned*)((const char*)(gbase) + (voff)[_i]), (LAS unsigned*)(lds + (bufoff) + ldsw + _i * 8192), 16, 0, 0); } while (0)
; #define PG8_LDA(dst, b, h) do { _Pragma("unroll") for (int m = 0; m < 4; ++m) _Pragma("unroll") for (int k = 0; k < 2; ++k) dst[m][k] = *(const LAS bf16x8*)(lds + PG8_SA(b, h) + aoff + m * 2048 + k * 1024); } while (0)
; #define PG8_MMA(ai, bj, At, Bt) do { __builtin_amdgcn_s_setprio(1); _Pragma("unroll") for (int m = 0; m < 4; ++m) _Pragma("unroll") for (int n = 0; n < 2; ++n) _Pragma("unroll") for (int k = 0; k < 2; ++k) \
;         acc[ai][bj][m][n] = __builtin_amdgcn_mfma_f32_16x16x32_bf16(Bt[n][k], At[m][k], acc[ai][bj][m][n], 0, 0, 0); __builtin_amdgcn_s_setprio(0); } while (0)
; #define PG8_WAIT_V(n) asm volatile("s_waitcnt vmcnt(" #n ")" ::: "memory")
; #define PG8_WAIT_L(n) asm volatile("s_waitcnt lgkmcnt(" #n ")" ::: "memory")
; #define PG8_BAR __builtin_amdgcn_s_barrier()
; #define PG8_SCHED __builtin_amdgcn_sched_barrier(0)
; template <class Epi, class SchedT, bool ALIGN_EPI, bool SP2>
; __device__ __forceinline__ void gemm_phase(LAS unsigned char* lds, const int ldk, const int nt, const SchedT& S, const Epi& E) {
;     ...
;             PG8_WAIT_V(8); PG8_WAIT_L(0); PG8_BAR; PG8_MMA(0, 0, At, B0); PG8_MMA(0, 1, At, B1); PG8_BAR; PG8_SCHED;
;             PG8_LDA(At, 1, 1); PG8_STAGE(PG8_SB(1, 0), b3, voffB); PG8_STAGE(PG8_SB(1, 1), b3 + hstepB, voffB); PG8_STAGE(PG8_SA(1, 0), a3, voffA);
;             PG8_WAIT_V(8); PG8_WAIT_L(0); PG8_BAR; PG8_MMA(1, 0, At, B0); PG8_MMA(1, 1, At, B1); PG8_BAR; PG8_SCHED;
;     __device__ __forceinline__ void operator()(f32x4 (&acc)[2][2][4][2], const Unit& u, int wr, int wc, int fr, int fq) const {
;         const int row0 = u.pm * BM + wr * 64 + fr, col0 = u.pn * BM + wc * 64 + 8 * fq;
; #pragma unroll
;         for (int ai = 0; ai < 2; ++ai)
; #pragma unroll
;             for (int m = 0; m < 4; ++m) {
;                 const int row = row0 + ai * HALF + m * 16; float sq = 0.f;
; #pragma unroll
;                 for (int bj = 0; bj < 2; ++bj) {
;                     const size_t off = (size_t)row * D + col0 + bj * 32;
;                     const u32x4 xw = *(const u32x4*)(xin + off);
	s_add_i32 s12, s64, s52
	v_lshl_add_u64 v[144:145], v[144:145], 0, s[24:25]
	s_mov_b32 m0, s12
	ds_read_b128 v[190:193], v149 offset:49152
	ds_read_b128 v[194:197], v149 offset:50176
	ds_read_b128 v[198:201], v149 offset:51200
	ds_read_b128 v[202:205], v149 offset:52224
	ds_read_b128 v[206:209], v149 offset:53248
	ds_read_b128 v[210:213], v149 offset:54272
	ds_read_b128 v[214:217], v149 offset:55296
	ds_read_b128 v[218:221], v149 offset:56320
	global_load_lds_dwordx4 v[144:145], off
	s_add_i32 m0, s12, 0x2000
	s_add_u32 s12, s44, 0x56080
	v_lshl_add_u64 v[144:145], v[222:223], 0, s[24:25]
	s_addc_u32 s13, s45, 0
	s_add_i32 s44, s65, s52
	global_load_lds_dwordx4 v[144:145], off
	v_lshl_add_u64 v[144:145], s[12:13], 0, v[0:1]
	s_mov_b32 m0, s44
	s_nop 0
	global_load_lds_dwordx4 v[144:145], off
	v_lshl_add_u64 v[144:145], s[12:13], 0, v[134:135]
	s_add_i32 m0, s44, 0x2000
	s_nop 0
	global_load_lds_dwordx4 v[144:145], off
	v_lshl_add_u64 v[144:145], v[224:225], 0, s[24:25]
	s_mov_b32 m0, s58
	s_nop 0
	global_load_lds_dwordx4 v[144:145], off
	v_lshl_add_u64 v[144:145], v[226:227], 0, s[24:25]
	s_mov_b32 m0, s59
	s_nop 0
	global_load_lds_dwordx4 v[144:145], off
	s_waitcnt vmcnt(8)
	s_waitcnt lgkmcnt(0)
	s_barrier
	s_waitcnt lgkmcnt(0)
	v_mfma_f32_16x16x32_bf16 v[62:65], v[140:143], v[190:193], v[62:65]
	v_mfma_f32_16x16x32_bf16 v[58:61], v[154:157], v[190:193], v[58:61]
	v_mfma_f32_16x16x32_bf16 v[46:49], v[140:143], v[198:201], v[46:49]
	v_mfma_f32_16x16x32_bf16 v[42:45], v[154:157], v[198:201], v[42:45]
	v_mfma_f32_16x16x32_bf16 v[30:33], v[140:143], v[206:209], v[30:33]
	v_mfma_f32_16x16x32_bf16 v[26:29], v[154:157], v[206:209], v[26:29]
	v_mfma_f32_16x16x32_bf16 v[14:17], v[140:143], v[214:217], v[14:17]
	v_mfma_f32_16x16x32_bf16 v[10:13], v[154:157], v[214:217], v[10:13]
	v_mfma_f32_16x16x32_bf16 v[62:65], v[150:153], v[194:197], v[62:65]
	v_mfma_f32_16x16x32_bf16 v[58:61], v[158:161], v[194:197], v[58:61]
	v_mfma_f32_16x16x32_bf16 v[46:49], v[150:153], v[202:205], v[46:49]
	v_mfma_f32_16x16x32_bf16 v[42:45], v[158:161], v[202:205], v[42:45]
	v_mfma_f32_16x16x32_bf16 v[30:33], v[150:153], v[210:213], v[30:33]
	v_mfma_f32_16x16x32_bf16 v[26:29], v[158:161], v[210:213], v[26:29]
	v_mfma_f32_16x16x32_bf16 v[14:17], v[150:153], v[218:221], v[14:17]
	v_mfma_f32_16x16x32_bf16 v[10:13], v[158:161], v[218:221], v[10:13]
	v_mfma_f32_16x16x32_bf16 v[54:57], v[174:177], v[190:193], v[54:57]
	v_mfma_f32_16x16x32_bf16 v[50:53], v[182:185], v[190:193], v[50:53]
	v_mfma_f32_16x16x32_bf16 v[38:41], v[174:177], v[198:201], v[38:41]
	v_mfma_f32_16x16x32_bf16 v[34:37], v[182:185], v[198:201], v[34:37]
	v_mfma_f32_16x16x32_bf16 v[22:25], v[174:177], v[206:209], v[22:25]
	v_mfma_f32_16x16x32_bf16 v[18:21], v[182:185], v[206:209], v[18:21]
	v_mfma_f32_16x16x32_bf16 v[6:9], v[174:177], v[214:217], v[6:9]
	v_mfma_f32_16x16x32_bf16 v[2:5], v[182:185], v[214:217], v[2:5]
	v_mfma_f32_16x16x32_bf16 v[54:57], v[178:181], v[194:197], v[54:57]
	v_mfma_f32_16x16x32_bf16 v[50:53], v[186:189], v[194:197], v[50:53]
	v_mfma_f32_16x16x32_bf16 v[38:41], v[178:181], v[202:205], v[38:41]
	v_mfma_f32_16x16x32_bf16 v[34:37], v[186:189], v[202:205], v[34:37]
	v_mfma_f32_16x16x32_bf16 v[22:25], v[178:181], v[210:213], v[22:25]
	v_mfma_f32_16x16x32_bf16 v[18:21], v[186:189], v[210:213], v[18:21]
	v_mfma_f32_16x16x32_bf16 v[6:9], v[178:181], v[218:221], v[6:9]
	v_mfma_f32_16x16x32_bf16 v[2:5], v[186:189], v[218:221], v[2:5]
	s_barrier
	s_add_i32 s83, s83, 2
	s_add_u32 s81, s81, 0x100
	s_addc_u32 s82, s82, 0
	s_cmpk_gt_u32 s83, 0x53
	s_mov_b64 s[12:13], s[16:17]
	s_cbranch_scc0 .LBB0_948
	v_lshl_add_u32 v142, s63, 8, v146
	v_lshl_or_b32 v140, s22, 8, v148
	v_lshlrev_b32_e32 v141, 12, v142
	v_lshl_add_u32 v150, v140, 1, v141
	v_add_u32_e32 v151, 0x10000, v150
	v_add_u32_e32 v152, 0x20000, v150
	v_add_u32_e32 v153, 0x30000, v150
	v_add_u32_e32 v154, 0x80000, v150
	v_add_u32_e32 v155, 0x90000, v150
	v_add_u32_e32 v156, 0xa0000, v150
	v_add_u32_e32 v157, 0xb0000, v150
	global_load_dwordx4 v[174:177], v150, s[20:21]
	global_load_dwordx4 v[178:181], v150, s[20:21] offset:64
	global_load_dwordx4 v[182:185], v151, s[20:21]
	global_load_dwordx4 v[186:189], v151, s[20:21] offset:64
	global_load_dwordx4 v[190:193], v152, s[20:21]
	global_load_dwordx4 v[194:197], v152, s[20:21] offset:64
	global_load_dwordx4 v[198:201], v153, s[20:21]
	global_load_dwordx4 v[202:205], v153, s[20:21] offset:64
	global_load_dwordx4 v[206:209], v154, s[20:21]
	global_load_dwordx4 v[210:213], v154, s[20:21] offset:64
	global_load_dwordx4 v[214:217], v155, s[20:21]
	global_load_dwordx4 v[218:221], v155, s[20:21] offset:64
	global_load_dwordx4 v[222:225], v156, s[20:21]
	global_load_dwordx4 v[226:229], v156, s[20:21] offset:64
	global_load_dwordx4 v[230:233], v157, s[20:21]
	global_load_dwordx4 v[234:237], v157, s[20:21] offset:64
	s_lshl_b32 s44, s22, 4
	s_lshl_b32 s45, s57, 2
	s_add_i32 s44, s44, s45
	v_lshl_add_u32 v158, v142, 7, s44
	v_add_u32_e32 v159, 0x1000, v158
	v_add_u32_e32 v160, 0x4000, v158
	v_add_u32_e32 v161, 0x5000, v158
	v_xor_b32_e32 v239, 16, v241
	v_xor_b32_e32 v252, 32, v241
	v_lshlrev_b32_e32 v239, 2, v239
	v_lshlrev_b32_e32 v252, 2, v252
	s_and_b64 vcc, exec, s[40:41]
	s_cbranch_vccz .LBB0_951
	s_barrier
	s_setprio 2
; __device__ __forceinline__ float bf_lo(unsigned w) { return __uint_as_float(w << 16); }
; __device__ __forceinline__ float bf_hi(unsigned w) { return __uint_as_float(w & 0xffff0000u); }
; __device__ __forceinline__ u32x4 pack8(f32x4 a, f32x4 b) { u32x4 w; w.x = cvt_pk_bf16(a[0], a[1]); w.y = cvt_pk_bf16(a[2], a[3]); w.z = cvt_pk_bf16(b[0], b[1]); w.w = cvt_pk_bf16(b[2], b[3]); return w; }
;     __device__ __forceinline__ void operator()(f32x4 (&acc)[2][2][4][2], const Unit& u, int wr, int wc, int fr, int fq) const {
;     ...
;                 const int row = row0 + ai * HALF + m * 16; float sq = 0.f;
; #pragma unroll
;                 for (int bj = 0; bj < 2; ++bj) {
;                     const size_t off = (size_t)row * D + col0 + bj * 32;
;                     const u32x4 xw = *(const u32x4*)(xin + off);
;                     const f32x4 v0 = acc[ai][bj][m][0] + (f32x4){bf_lo(xw.x), bf_hi(xw.x), bf_lo(xw.y), bf_hi(xw.y)}, v1 = acc[ai][bj][m][1] + (f32x4){bf_lo(xw.z), bf_hi(xw.z), bf_lo(xw.w), bf_hi(xw.w)};
;                     *(u32x4*)(xb + off) = pack8(v0, v1);
;                     sq += (v0[0] * v0[0] + v0[1] * v0[1]) + (v0[2] * v0[2] + v0[3] * v0[3]) + (v1[0] * v1[0] + v1[1] * v1[1]) + (v1[2] * v1[2] + v1[3] * v1[3]);
.LBB0_951:
	s_waitcnt vmcnt(15)
	v_lshlrev_b32_e32 v246, 16, v174
	v_and_b32_e32 v247, 0xffff0000, v174
	v_lshlrev_b32_e32 v248, 16, v175
	v_and_b32_e32 v249, 0xffff0000, v175
	v_pk_add_f32 v[126:127], v[126:127], v[246:247]
	v_pk_add_f32 v[128:129], v[128:129], v[248:249]
	v_lshlrev_b32_e32 v246, 16, v176
	v_and_b32_e32 v247, 0xffff0000, v176
	v_lshlrev_b32_e32 v248, 16, v177
	v_and_b32_e32 v249, 0xffff0000, v177
	v_pk_add_f32 v[122:123], v[122:123], v[246:247]
	v_pk_add_f32 v[124:125], v[124:125], v[248:249]
	v_cvt_pk_bf16_f32 v174, v126, v127
	v_cvt_pk_bf16_f32 v175, v128, v129
	v_cvt_pk_bf16_f32 v176, v122, v123
	v_cvt_pk_bf16_f32 v177, v124, v125
	global_store_dwordx4 v150, v[174:177], s[30:31]
	v_pk_mul_f32 v[250:251], v[126:127], v[126:127]
	v_pk_fma_f32 v[250:251], v[128:129], v[128:129], v[250:251]
	v_pk_fma_f32 v[250:251], v[122:123], v[122:123], v[250:251]
	v_pk_fma_f32 v[250:251], v[124:125], v[124:125], v[250:251]
	s_waitcnt vmcnt(15)
	v_lshlrev_b32_e32 v246, 16, v178
	v_and_b32_e32 v247, 0xffff0000, v178
	v_lshlrev_b32_e32 v248, 16, v179
	v_and_b32_e32 v249, 0xffff0000, v179
	v_pk_add_f32 v[118:119], v[118:119], v[246:247]
	v_pk_add_f32 v[120:121], v[120:121], v[248:249]
	v_lshlrev_b32_e32 v246, 16, v180
	v_and_b32_e32 v247, 0xffff0000, v180
	v_lshlrev_b32_e32 v248, 16, v181
	v_and_b32_e32 v249, 0xffff0000, v181
	v_pk_add_f32 v[114:115], v[114:115], v[246:247]
	v_pk_add_f32 v[116:117], v[116:117], v[248:249]
	v_cvt_pk_bf16_f32 v178, v118, v119
	v_cvt_pk_bf16_f32 v179, v120, v121
	v_cvt_pk_bf16_f32 v180, v114, v115
	v_cvt_pk_bf16_f32 v181, v116, v117
	global_store_dwordx4 v150, v[178:181], s[30:31] offset:64
	v_pk_fma_f32 v[250:251], v[118:119], v[118:119], v[250:251]
	v_pk_fma_f32 v[250:251], v[120:121], v[120:121], v[250:251]
	v_pk_fma_f32 v[250:251], v[114:115], v[114:115], v[250:251]
	v_pk_fma_f32 v[250:251], v[116:117], v[116:117], v[250:251]
	v_add_f32_e32 v140, v250, v251
	s_waitcnt vmcnt(15)
	v_lshlrev_b32_e32 v246, 16, v182
	v_and_b32_e32 v247, 0xffff0000, v182
	v_lshlrev_b32_e32 v248, 16, v183
	v_and_b32_e32 v249, 0xffff0000, v183
	v_pk_add_f32 v[110:111], v[110:111], v[246:247]
	v_pk_add_f32 v[112:113], v[112:113], v[248:249]
	v_lshlrev_b32_e32 v246, 16, v184
	v_and_b32_e32 v247, 0xffff0000, v184
	v_lshlrev_b32_e32 v248, 16, v185
	v_and_b32_e32 v249, 0xffff0000, v185
	v_pk_add_f32 v[106:107], v[106:107], v[246:247]
	v_pk_add_f32 v[108:109], v[108:109], v[248:249]
	v_cvt_pk_bf16_f32 v182, v110, v111
	v_cvt_pk_bf16_f32 v183, v112, v113
	v_cvt_pk_bf16_f32 v184, v106, v107
	v_cvt_pk_bf16_f32 v185, v108, v109
	global_store_dwordx4 v151, v[182:185], s[30:31]
	v_pk_mul_f32 v[250:251], v[110:111], v[110:111]
	v_pk_fma_f32 v[250:251], v[112:113], v[112:113], v[250:251]
	v_pk_fma_f32 v[250:251], v[106:107], v[106:107], v[250:251]
	v_pk_fma_f32 v[250:251], v[108:109], v[108:109], v[250:251]
	s_waitcnt vmcnt(15)
	v_lshlrev_b32_e32 v246, 16, v186
	v_and_b32_e32 v247, 0xffff0000, v186
	v_lshlrev_b32_e32 v248, 16, v187
	v_and_b32_e32 v249, 0xffff0000, v187
	v_pk_add_f32 v[102:103], v[102:103], v[246:247]
	v_pk_add_f32 v[104:105], v[104:105], v[248:249]
	v_lshlrev_b32_e32 v246, 16, v188
	v_and_b32_e32 v247, 0xffff0000, v188
	v_lshlrev_b32_e32 v248, 16, v189
	v_and_b32_e32 v249, 0xffff0000, v189
	v_pk_add_f32 v[98:99], v[98:99], v[246:247]
	v_pk_add_f32 v[100:101], v[100:101], v[248:249]
	v_cvt_pk_bf16_f32 v186, v102, v103
	v_cvt_pk_bf16_f32 v187, v104, v105
	v_cvt_pk_bf16_f32 v188, v98, v99
	v_cvt_pk_bf16_f32 v189, v100, v101
	global_store_dwordx4 v151, v[186:189], s[30:31] offset:64
	v_pk_fma_f32 v[250:251], v[102:103], v[102:103], v[250:251]
	v_pk_fma_f32 v[250:251], v[104:105], v[104:105], v[250:251]
	v_pk_fma_f32 v[250:251], v[98:99], v[98:99], v[250:251]
	v_pk_fma_f32 v[250:251], v[100:101], v[100:101], v[250:251]
	v_add_f32_e32 v141, v250, v251
	s_waitcnt vmcnt(15)
	v_lshlrev_b32_e32 v246, 16, v190
	v_and_b32_e32 v247, 0xffff0000, v190
	v_lshlrev_b32_e32 v248, 16, v191
	v_and_b32_e32 v249, 0xffff0000, v191
	v_pk_add_f32 v[94:95], v[94:95], v[246:247]
	v_pk_add_f32 v[96:97], v[96:97], v[248:249]
	v_lshlrev_b32_e32 v246, 16, v192
	v_and_b32_e32 v247, 0xffff0000, v192
	v_lshlrev_b32_e32 v248, 16, v193
	v_and_b32_e32 v249, 0xffff0000, v193
	v_pk_add_f32 v[90:91], v[90:91], v[246:247]
	v_pk_add_f32 v[92:93], v[92:93], v[248:249]
	v_cvt_pk_bf16_f32 v190, v94, v95
	v_cvt_pk_bf16_f32 v191, v96, v97
	v_cvt_pk_bf16_f32 v192, v90, v91
	v_cvt_pk_bf16_f32 v193, v92, v93
	global_store_dwordx4 v152, v[190:193], s[30:31]
	v_pk_mul_f32 v[250:251], v[94:95], v[94:95]
	v_pk_fma_f32 v[250:251], v[96:97], v[96:97], v[250:251]
	v_pk_fma_f32 v[250:251], v[90:91], v[90:91], v[250:251]
	v_pk_fma_f32 v[250:251], v[92:93], v[92:93], v[250:251]
	s_waitcnt vmcnt(15)
	v_lshlrev_b32_e32 v246, 16, v194
	v_and_b32_e32 v247, 0xffff0000, v194
	v_lshlrev_b32_e32 v248, 16, v195
	v_and_b32_e32 v249, 0xffff0000, v195
	v_pk_add_f32 v[86:87], v[86:87], v[246:247]
	v_pk_add_f32 v[88:89], v[88:89], v[248:249]
	v_lshlrev_b32_e32 v246, 16, v196
	v_and_b32_e32 v247, 0xffff0000, v196
	v_lshlrev_b32_e32 v248, 16, v197
	v_and_b32_e32 v249, 0xffff0000, v197
	v_pk_add_f32 v[82:83], v[82:83], v[246:247]
	v_pk_add_f32 v[84:85], v[84:85], v[248:249]
	v_cvt_pk_bf16_f32 v194, v86, v87
	v_cvt_pk_bf16_f32 v195, v88, v89
	v_cvt_pk_bf16_f32 v196, v82, v83
	v_cvt_pk_bf16_f32 v197, v84, v85
	global_store_dwordx4 v152, v[194:197], s[30:31] offset:64
	v_pk_fma_f32 v[250:251], v[86:87], v[86:87], v[250:251]
	v_pk_fma_f32 v[250:251], v[88:89], v[88:89], v[250:251]
	v_pk_fma_f32 v[250:251], v[82:83], v[82:83], v[250:251]
	v_pk_fma_f32 v[250:251], v[84:85], v[84:85], v[250:251]
	v_add_f32_e32 v142, v250, v251
	s_waitcnt vmcnt(15)
; __device__ __forceinline__ float bf_lo(unsigned w) { return __uint_as_float(w << 16); }
; __device__ __forceinline__ float bf_hi(unsigned w) { return __uint_as_float(w & 0xffff0000u); }
; __device__ __forceinline__ u32x4 pack8(f32x4 a, f32x4 b) { u32x4 w; w.x = cvt_pk_bf16(a[0], a[1]); w.y = cvt_pk_bf16(a[2], a[3]); w.z = cvt_pk_bf16(b[0], b[1]); w.w = cvt_pk_bf16(b[2], b[3]); return w; }
;     __device__ __forceinline__ void operator()(f32x4 (&acc)[2][2][4][2], const Unit& u, int wr, int wc, int fr, int fq) const {
;     ...
;                 const int row = row0 + ai * HALF + m * 16; float sq = 0.f;
; #pragma unroll
;                 for (int bj = 0; bj < 2; ++bj) {
;                     const size_t off = (size_t)row * D + col0 + bj * 32;
;                     const u32x4 xw = *(const u32x4*)(xin + off);
;                     const f32x4 v0 = acc[ai][bj][m][0] + (f32x4){bf_lo(xw.x), bf_hi(xw.x), bf_lo(xw.y), bf_hi(xw.y)}, v1 = acc[ai][bj][m][1] + (f32x4){bf_lo(xw.z), bf_hi(xw.z), bf_lo(xw.w), bf_hi(xw.w)};
;                     *(u32x4*)(xb + off) = pack8(v0, v1);
;                     sq += (v0[0] * v0[0] + v0[1] * v0[1]) + (v0[2] * v0[2] + v0[3] * v0[3]) + (v1[0] * v1[0] + v1[1] * v1[1]) + (v1[2] * v1[2] + v1[3] * v1[3]);
	v_lshlrev_b32_e32 v246, 16, v198
	v_and_b32_e32 v247, 0xffff0000, v198
	v_lshlrev_b32_e32 v248, 16, v199
	v_and_b32_e32 v249, 0xffff0000, v199
	v_pk_add_f32 v[78:79], v[78:79], v[246:247]
	v_pk_add_f32 v[80:81], v[80:81], v[248:249]
	v_lshlrev_b32_e32 v246, 16, v200
	v_and_b32_e32 v247, 0xffff0000, v200
	v_lshlrev_b32_e32 v248, 16, v201
	v_and_b32_e32 v249, 0xffff0000, v201
	v_pk_add_f32 v[74:75], v[74:75], v[246:247]
	v_pk_add_f32 v[76:77], v[76:77], v[248:249]
	v_cvt_pk_bf16_f32 v198, v78, v79
	v_cvt_pk_bf16_f32 v199, v80, v81
	v_cvt_pk_bf16_f32 v200, v74, v75
	v_cvt_pk_bf16_f32 v201, v76, v77
	global_store_dwordx4 v153, v[198:201], s[30:31]
	v_pk_mul_f32 v[250:251], v[78:79], v[78:79]
	v_pk_fma_f32 v[250:251], v[80:81], v[80:81], v[250:251]
	v_pk_fma_f32 v[250:251], v[74:75], v[74:75], v[250:251]
	v_pk_fma_f32 v[250:251], v[76:77], v[76:77], v[250:251]
	s_waitcnt vmcnt(15)
	v_lshlrev_b32_e32 v246, 16, v202
	v_and_b32_e32 v247, 0xffff0000, v202
	v_lshlrev_b32_e32 v248, 16, v203
	v_and_b32_e32 v249, 0xffff0000, v203
	v_pk_add_f32 v[70:71], v[70:71], v[246:247]
	v_pk_add_f32 v[72:73], v[72:73], v[248:249]
	v_lshlrev_b32_e32 v246, 16, v204
	v_and_b32_e32 v247, 0xffff0000, v204
	v_lshlrev_b32_e32 v248, 16, v205
	v_and_b32_e32 v249, 0xffff0000, v205
	v_pk_add_f32 v[66:67], v[66:67], v[246:247]
	v_pk_add_f32 v[68:69], v[68:69], v[248:249]
	v_cvt_pk_bf16_f32 v202, v70, v71
	v_cvt_pk_bf16_f32 v203, v72, v73
	v_cvt_pk_bf16_f32 v204, v66, v67
	v_cvt_pk_bf16_f32 v205, v68, v69
	global_store_dwordx4 v153, v[202:205], s[30:31] offset:64
	v_pk_fma_f32 v[250:251], v[70:71], v[70:71], v[250:251]
	v_pk_fma_f32 v[250:251], v[72:73], v[72:73], v[250:251]
	v_pk_fma_f32 v[250:251], v[66:67], v[66:67], v[250:251]
	v_pk_fma_f32 v[250:251], v[68:69], v[68:69], v[250:251]
	v_add_f32_e32 v143, v250, v251
	s_waitcnt vmcnt(15)
	v_lshlrev_b32_e32 v246, 16, v206
	v_and_b32_e32 v247, 0xffff0000, v206
	v_lshlrev_b32_e32 v248, 16, v207
	v_and_b32_e32 v249, 0xffff0000, v207
	v_pk_add_f32 v[62:63], v[62:63], v[246:247]
	v_pk_add_f32 v[64:65], v[64:65], v[248:249]
	v_lshlrev_b32_e32 v246, 16, v208
	v_and_b32_e32 v247, 0xffff0000, v208
	v_lshlrev_b32_e32 v248, 16, v209
	v_and_b32_e32 v249, 0xffff0000, v209
	v_pk_add_f32 v[58:59], v[58:59], v[246:247]
	v_pk_add_f32 v[60:61], v[60:61], v[248:249]
	v_cvt_pk_bf16_f32 v206, v62, v63
	v_cvt_pk_bf16_f32 v207, v64, v65
	v_cvt_pk_bf16_f32 v208, v58, v59
	v_cvt_pk_bf16_f32 v209, v60, v61
	global_store_dwordx4 v154, v[206:209], s[30:31]
	v_pk_mul_f32 v[250:251], v[62:63], v[62:63]
	v_pk_fma_f32 v[250:251], v[64:65], v[64:65], v[250:251]
	v_pk_fma_f32 v[250:251], v[58:59], v[58:59], v[250:251]
	v_pk_fma_f32 v[250:251], v[60:61], v[60:61], v[250:251]
	s_waitcnt vmcnt(15)
	v_lshlrev_b32_e32 v246, 16, v210
	v_and_b32_e32 v247, 0xffff0000, v210
	v_lshlrev_b32_e32 v248, 16, v211
	v_and_b32_e32 v249, 0xffff0000, v211
	v_pk_add_f32 v[54:55], v[54:55], v[246:247]
	v_pk_add_f32 v[56:57], v[56:57], v[248:249]
	v_lshlrev_b32_e32 v246, 16, v212
	v_and_b32_e32 v247, 0xffff0000, v212
	v_lshlrev_b32_e32 v248, 16, v213
	v_and_b32_e32 v249, 0xffff0000, v213
	v_pk_add_f32 v[50:51], v[50:51], v[246:247]
	v_pk_add_f32 v[52:53], v[52:53], v[248:249]
	v_cvt_pk_bf16_f32 v210, v54, v55
	v_cvt_pk_bf16_f32 v211, v56, v57
	v_cvt_pk_bf16_f32 v212, v50, v51
	v_cvt_pk_bf16_f32 v213, v52, v53
	global_store_dwordx4 v154, v[210:213], s[30:31] offset:64
	v_pk_fma_f32 v[250:251], v[54:55], v[54:55], v[250:251]
	v_pk_fma_f32 v[250:251], v[56:57], v[56:57], v[250:251]
	v_pk_fma_f32 v[250:251], v[50:51], v[50:51], v[250:251]
	v_pk_fma_f32 v[250:251], v[52:53], v[52:53], v[250:251]
	v_add_f32_e32 v144, v250, v251
	s_waitcnt vmcnt(15)
	v_lshlrev_b32_e32 v246, 16, v214
	v_and_b32_e32 v247, 0xffff0000, v214
	v_lshlrev_b32_e32 v248, 16, v215
	v_and_b32_e32 v249, 0xffff0000, v215
	v_pk_add_f32 v[46:47], v[46:47], v[246:247]
	v_pk_add_f32 v[48:49], v[48:49], v[248:249]
	v_lshlrev_b32_e32 v246, 16, v216
	v_and_b32_e32 v247, 0xffff0000, v216
	v_lshlrev_b32_e32 v248, 16, v217
	v_and_b32_e32 v249, 0xffff0000, v217
	v_pk_add_f32 v[42:43], v[42:43], v[246:247]
	v_pk_add_f32 v[44:45], v[44:45], v[248:249]
	v_cvt_pk_bf16_f32 v214, v46, v47
	v_cvt_pk_bf16_f32 v215, v48, v49
	v_cvt_pk_bf16_f32 v216, v42, v43
	v_cvt_pk_bf16_f32 v217, v44, v45
	global_store_dwordx4 v155, v[214:217], s[30:31]
	v_pk_mul_f32 v[250:251], v[46:47], v[46:47]
	v_pk_fma_f32 v[250:251], v[48:49], v[48:49], v[250:251]
	v_pk_fma_f32 v[250:251], v[42:43], v[42:43], v[250:251]
	v_pk_fma_f32 v[250:251], v[44:45], v[44:45], v[250:251]
	s_waitcnt vmcnt(15)
	v_lshlrev_b32_e32 v246, 16, v218
	v_and_b32_e32 v247, 0xffff0000, v218
	v_lshlrev_b32_e32 v248, 16, v219
	v_and_b32_e32 v249, 0xffff0000, v219
	v_pk_add_f32 v[38:39], v[38:39], v[246:247]
	v_pk_add_f32 v[40:41], v[40:41], v[248:249]
	v_lshlrev_b32_e32 v246, 16, v220
	v_and_b32_e32 v247, 0xffff0000, v220
	v_lshlrev_b32_e32 v248, 16, v221
	v_and_b32_e32 v249, 0xffff0000, v221
	v_pk_add_f32 v[34:35], v[34:35], v[246:247]
	v_pk_add_f32 v[36:37], v[36:37], v[248:249]
	v_cvt_pk_bf16_f32 v218, v38, v39
	v_cvt_pk_bf16_f32 v219, v40, v41
	v_cvt_pk_bf16_f32 v220, v34, v35
	v_cvt_pk_bf16_f32 v221, v36, v37
	global_store_dwordx4 v155, v[218:221], s[30:31] offset:64
	v_pk_fma_f32 v[250:251], v[38:39], v[38:39], v[250:251]
	v_pk_fma_f32 v[250:251], v[40:41], v[40:41], v[250:251]
	v_pk_fma_f32 v[250:251], v[34:35], v[34:35], v[250:251]
	v_pk_fma_f32 v[250:251], v[36:37], v[36:37], v[250:251]
	v_add_f32_e32 v145, v250, v251
	s_waitcnt vmcnt(15)
; __device__ __forceinline__ float bf_lo(unsigned w) { return __uint_as_float(w << 16); }
; __device__ __forceinline__ float bf_hi(unsigned w) { return __uint_as_float(w & 0xffff0000u); }
; __device__ __forceinline__ u32x4 pack8(f32x4 a, f32x4 b) { u32x4 w; w.x = cvt_pk_bf16(a[0], a[1]); w.y = cvt_pk_bf16(a[2], a[3]); w.z = cvt_pk_bf16(b[0], b[1]); w.w = cvt_pk_bf16(b[2], b[3]); return w; }
; #define PG8_BAR __builtin_amdgcn_s_barrier()
; template <class Epi, class SchedT, bool ALIGN_EPI, bool SP2>
; __device__ __forceinline__ void gemm_phase(LAS unsigned char* lds, const int ldk, const int nt, const SchedT& S, const Epi& E) {
;     ...
;         if (!has_next) break;
;         if (!(SchedT::kMode == 2 && cur.kind == 0)) {
; #pragma unroll
;         for (int a = 0; a < 2; ++a)
; #pragma unroll
;             for (int b = 0; b < 2; ++b)
; #pragma unroll
;                 for (int m = 0; m < 4; ++m)
; #pragma unroll
;                     for (int n = 0; n < 2; ++n) acc[a][b][m][n] = (f32x4){0.f, 0.f, 0.f, 0.f};
;         }
;         cur = nxt; cA = nA; cB = nB; ++ui;
;         if constexpr (ALIGN_EPI) { if (wr == 1) PG8_BAR; }
;     __device__ __forceinline__ void operator()(f32x4 (&acc)[2][2][4][2], const Unit& u, int wr, int wc, int fr, int fq) const {
;     ...
;                 const int row = row0 + ai * HALF + m * 16; float sq = 0.f;
; #pragma unroll
;                 for (int bj = 0; bj < 2; ++bj) {
;                     const size_t off = (size_t)row * D + col0 + bj * 32;
;                     const u32x4 xw = *(const u32x4*)(xin + off);
;                     const f32x4 v0 = acc[ai][bj][m][0] + (f32x4){bf_lo(xw.x), bf_hi(xw.x), bf_lo(xw.y), bf_hi(xw.y)}, v1 = acc[ai][bj][m][1] + (f32x4){bf_lo(xw.z), bf_hi(xw.z), bf_lo(xw.w), bf_hi(xw.w)};
;                     *(u32x4*)(xb + off) = pack8(v0, v1);
;                     sq += (v0[0] * v0[0] + v0[1] * v0[1]) + (v0[2] * v0[2] + v0[3] * v0[3]) + (v1[0] * v1[0] + v1[1] * v1[1]) + (v1[2] * v1[2] + v1[3] * v1[3]);
;                 }
;                 sq += __shfl_xor(sq, 16); sq += __shfl_xor(sq, 32);
;                 if (fq == 0) ss[(size_t)row * 32 + u.pn * 4 + wc] = sq;
	v_lshlrev_b32_e32 v246, 16, v222
	v_and_b32_e32 v247, 0xffff0000, v222
	v_lshlrev_b32_e32 v248, 16, v223
	v_and_b32_e32 v249, 0xffff0000, v223
	v_pk_add_f32 v[30:31], v[30:31], v[246:247]
	v_pk_add_f32 v[32:33], v[32:33], v[248:249]
	v_lshlrev_b32_e32 v246, 16, v224
	v_and_b32_e32 v247, 0xffff0000, v224
	v_lshlrev_b32_e32 v248, 16, v225
	v_and_b32_e32 v249, 0xffff0000, v225
	v_pk_add_f32 v[26:27], v[26:27], v[246:247]
	v_pk_add_f32 v[28:29], v[28:29], v[248:249]
	v_cvt_pk_bf16_f32 v222, v30, v31
	v_cvt_pk_bf16_f32 v223, v32, v33
	v_cvt_pk_bf16_f32 v224, v26, v27
	v_cvt_pk_bf16_f32 v225, v28, v29
	global_store_dwordx4 v156, v[222:225], s[30:31]
	v_pk_mul_f32 v[250:251], v[30:31], v[30:31]
	v_pk_fma_f32 v[250:251], v[32:33], v[32:33], v[250:251]
	v_pk_fma_f32 v[250:251], v[26:27], v[26:27], v[250:251]
	v_pk_fma_f32 v[250:251], v[28:29], v[28:29], v[250:251]
	s_waitcnt vmcnt(15)
	v_lshlrev_b32_e32 v246, 16, v226
	v_and_b32_e32 v247, 0xffff0000, v226
	v_lshlrev_b32_e32 v248, 16, v227
	v_and_b32_e32 v249, 0xffff0000, v227
	v_pk_add_f32 v[22:23], v[22:23], v[246:247]
	v_pk_add_f32 v[24:25], v[24:25], v[248:249]
	v_lshlrev_b32_e32 v246, 16, v228
	v_and_b32_e32 v247, 0xffff0000, v228
	v_lshlrev_b32_e32 v248, 16, v229
	v_and_b32_e32 v249, 0xffff0000, v229
	v_pk_add_f32 v[18:19], v[18:19], v[246:247]
	v_pk_add_f32 v[20:21], v[20:21], v[248:249]
	v_cvt_pk_bf16_f32 v226, v22, v23
	v_cvt_pk_bf16_f32 v227, v24, v25
	v_cvt_pk_bf16_f32 v228, v18, v19
	v_cvt_pk_bf16_f32 v229, v20, v21
	global_store_dwordx4 v156, v[226:229], s[30:31] offset:64
	v_pk_fma_f32 v[250:251], v[22:23], v[22:23], v[250:251]
	v_pk_fma_f32 v[250:251], v[24:25], v[24:25], v[250:251]
	v_pk_fma_f32 v[250:251], v[18:19], v[18:19], v[250:251]
	v_pk_fma_f32 v[250:251], v[20:21], v[20:21], v[250:251]
	v_add_f32_e32 v162, v250, v251
	s_waitcnt vmcnt(15)
	v_lshlrev_b32_e32 v246, 16, v230
	v_and_b32_e32 v247, 0xffff0000, v230
	v_lshlrev_b32_e32 v248, 16, v231
	v_and_b32_e32 v249, 0xffff0000, v231
	v_pk_add_f32 v[14:15], v[14:15], v[246:247]
	v_pk_add_f32 v[16:17], v[16:17], v[248:249]
	v_lshlrev_b32_e32 v246, 16, v232
	v_and_b32_e32 v247, 0xffff0000, v232
	v_lshlrev_b32_e32 v248, 16, v233
	v_and_b32_e32 v249, 0xffff0000, v233
	v_pk_add_f32 v[10:11], v[10:11], v[246:247]
	v_pk_add_f32 v[12:13], v[12:13], v[248:249]
	v_cvt_pk_bf16_f32 v230, v14, v15
	v_cvt_pk_bf16_f32 v231, v16, v17
	v_cvt_pk_bf16_f32 v232, v10, v11
	v_cvt_pk_bf16_f32 v233, v12, v13
	global_store_dwordx4 v157, v[230:233], s[30:31]
	v_pk_mul_f32 v[250:251], v[14:15], v[14:15]
	v_pk_fma_f32 v[250:251], v[16:17], v[16:17], v[250:251]
	v_pk_fma_f32 v[250:251], v[10:11], v[10:11], v[250:251]
	v_pk_fma_f32 v[250:251], v[12:13], v[12:13], v[250:251]
	s_waitcnt vmcnt(15)
	v_lshlrev_b32_e32 v246, 16, v234
	v_and_b32_e32 v247, 0xffff0000, v234
	v_lshlrev_b32_e32 v248, 16, v235
	v_and_b32_e32 v249, 0xffff0000, v235
	v_pk_add_f32 v[6:7], v[6:7], v[246:247]
	v_pk_add_f32 v[8:9], v[8:9], v[248:249]
	v_lshlrev_b32_e32 v246, 16, v236
	v_and_b32_e32 v247, 0xffff0000, v236
	v_lshlrev_b32_e32 v248, 16, v237
	v_and_b32_e32 v249, 0xffff0000, v237
	v_pk_add_f32 v[2:3], v[2:3], v[246:247]
	v_pk_add_f32 v[4:5], v[4:5], v[248:249]
	v_cvt_pk_bf16_f32 v234, v6, v7
	v_cvt_pk_bf16_f32 v235, v8, v9
	v_cvt_pk_bf16_f32 v236, v2, v3
	v_cvt_pk_bf16_f32 v237, v4, v5
	global_store_dwordx4 v157, v[234:237], s[30:31] offset:64
	v_pk_fma_f32 v[250:251], v[6:7], v[6:7], v[250:251]
	v_pk_fma_f32 v[250:251], v[8:9], v[8:9], v[250:251]
	v_pk_fma_f32 v[250:251], v[2:3], v[2:3], v[250:251]
	v_pk_fma_f32 v[250:251], v[4:5], v[4:5], v[250:251]
	v_add_f32_e32 v238, v250, v251
	ds_bpermute_b32 v174, v239, v140
	ds_bpermute_b32 v175, v239, v141
	ds_bpermute_b32 v176, v239, v142
	ds_bpermute_b32 v177, v239, v143
	ds_bpermute_b32 v178, v239, v144
	ds_bpermute_b32 v179, v239, v145
	ds_bpermute_b32 v180, v239, v162
	ds_bpermute_b32 v181, v239, v238
	s_waitcnt lgkmcnt(0)
	v_add_f32_e32 v140, v140, v174
	v_add_f32_e32 v141, v141, v175
	v_add_f32_e32 v142, v142, v176
	v_add_f32_e32 v143, v143, v177
	v_add_f32_e32 v144, v144, v178
	v_add_f32_e32 v145, v145, v179
	v_add_f32_e32 v162, v162, v180
	v_add_f32_e32 v238, v238, v181
	ds_bpermute_b32 v174, v252, v140
	ds_bpermute_b32 v175, v252, v141
	ds_bpermute_b32 v176, v252, v142
	ds_bpermute_b32 v177, v252, v143
	ds_bpermute_b32 v178, v252, v144
	ds_bpermute_b32 v179, v252, v145
	ds_bpermute_b32 v180, v252, v162
	ds_bpermute_b32 v181, v252, v238
	s_waitcnt lgkmcnt(0)
	v_add_f32_e32 v140, v140, v174
	v_add_f32_e32 v141, v141, v175
	v_add_f32_e32 v142, v142, v176
	v_add_f32_e32 v143, v143, v177
	v_add_f32_e32 v144, v144, v178
	v_add_f32_e32 v145, v145, v179
	v_add_f32_e32 v162, v162, v180
	v_add_f32_e32 v238, v238, v181
	s_and_saveexec_b64 s[12:13], s[36:37]
	global_store_dword v158, v140, s[34:35]
	global_store_dword v158, v141, s[34:35] offset:2048
	global_store_dword v159, v142, s[34:35]
	global_store_dword v159, v143, s[34:35] offset:2048
	global_store_dword v160, v144, s[34:35]
	global_store_dword v160, v145, s[34:35] offset:2048
	global_store_dword v161, v162, s[34:35]
	global_store_dword v161, v238, s[34:35] offset:2048
	s_mov_b32 s65, 0x10000
	s_or_b64 exec, exec, s[12:13]
	s_and_b64 vcc, exec, s[38:39]
	s_mov_b64 s[12:13], -1
	s_cbranch_vccnz .LBB0_942
	s_setprio 0
	s_andn2_b64 vcc, exec, s[18:19]
	s_cbranch_vccnz .LBB0_941
	s_barrier
	s_setprio 1
	s_branch .LBB0_941
